# 128x256 tile K-loops (GU1, INM, GU2) rewritten: LDS-DMA BK=32 3-stage ring, lookahead 2, A fragments double-buffered, deferred MFMAs behind the barrier; compiler epilogues kept; s_setprio 3 on the pro
# speedup vs baseline: 1.1187x; 1.0206x over previous
.LBB0_96:
	s_andn2_b64 vcc, exec, s[2:3]
	s_cbranch_vccnz .LBB0_90
	v_readlane_b32 s2, v253, 4
	v_readlane_b32 s3, v253, 5
	s_lshl_b32 s13, s54, 18
	s_add_u32 s2, s2, s13
	s_addc_u32 s3, s3, 0
	s_lshl_b32 s13, s56, 19
	s_add_u32 s4, s50, 0x4490000
	s_addc_u32 s5, s51, 0
	s_add_u32 s4, s4, s13
	s_addc_u32 s5, s5, 0
	v_and_b32_e32 v152, 63, v216
	v_lshrrev_b32_e32 v153, 6, v216
	v_lshrrev_b32_e32 v154, 2, v152
	v_and_b32_e32 v155, 3, v152
	v_readfirstlane_b32 s11, v153
	v_lshrrev_b32_e32 v156, 3, v154
	v_mul_u32_u24_e32 v156, 3, v156
	v_xor_b32_e32 v156, v155, v156
	v_lshlrev_b32_e32 v156, 4, v156
	v_lshl_add_u32 v157, v153, 5, v154
	v_lshl_add_u32 v203, v157, 11, v156
	v_add_u32_e32 v204, 0x8000, v203
	v_lshl_add_u32 v157, v153, 6, v154
	v_lshl_add_u32 v205, v157, 11, v156
	v_add_u32_e32 v206, 0x8000, v205
	v_add_u32_e32 v207, 0x10000, v205
	v_add_u32_e32 v208, 0x18000, v205
	v_and_b32_e32 v158, 15, v152
	v_lshrrev_b32_e32 v159, 4, v152
	v_lshrrev_b32_e32 v160, 3, v158
	v_mul_u32_u24_e32 v160, 3, v160
	v_xor_b32_e32 v160, v159, v160
	v_lshlrev_b32_e32 v160, 4, v160
	v_lshl_add_u32 v160, v158, 6, v160
	v_lshrrev_b32_e32 v161, 1, v153
	v_and_b32_e32 v162, 1, v153
	v_lshl_add_u32 v209, v161, 12, v160
	v_lshl_add_u32 v210, v162, 13, v160
	s_lshl_b32 s12, s11, 12
	s_lshl_b32 s11, s11, 11
	s_add_u32 m0, s11, 0x0
	s_nop 0
	global_load_lds_dwordx4 v203, s[2:3]
	s_add_u32 m0, s11, 0x400
	s_nop 0
	global_load_lds_dwordx4 v204, s[2:3]
	s_add_u32 m0, s12, 0x2000
	s_nop 0
	global_load_lds_dwordx4 v205, s[4:5]
	s_add_u32 m0, s12, 0x2400
	s_nop 0
	global_load_lds_dwordx4 v206, s[4:5]
	s_add_u32 m0, s12, 0x2800
	s_nop 0
	global_load_lds_dwordx4 v207, s[4:5]
	s_add_u32 m0, s12, 0x2c00
	s_nop 0
	global_load_lds_dwordx4 v208, s[4:5]
	s_add_u32 s2, s2, 0x40
	s_addc_u32 s3, s3, 0
	s_add_u32 s4, s4, 0x40
	s_addc_u32 s5, s5, 0
	s_add_u32 m0, s11, 0x6000
	s_nop 0
	global_load_lds_dwordx4 v203, s[2:3]
	s_add_u32 m0, s11, 0x6400
	s_nop 0
	global_load_lds_dwordx4 v204, s[2:3]
	s_add_u32 m0, s12, 0x8000
	s_nop 0
	global_load_lds_dwordx4 v205, s[4:5]
	s_add_u32 m0, s12, 0x8400
	s_nop 0
	global_load_lds_dwordx4 v206, s[4:5]
	s_add_u32 m0, s12, 0x8800
	s_nop 0
	global_load_lds_dwordx4 v207, s[4:5]
	s_add_u32 m0, s12, 0x8c00
	s_nop 0
	global_load_lds_dwordx4 v208, s[4:5]
	s_add_u32 s2, s2, 0x40
	s_addc_u32 s3, s3, 0
	s_add_u32 s4, s4, 0x40
	s_addc_u32 s5, s5, 0
	v_mov_b32_e32 v172, 0
	v_mov_b32_e32 v173, 0
	v_mov_b32_e32 v174, 0
	v_mov_b32_e32 v175, 0
	v_mov_b32_e32 v168, 0
	v_mov_b32_e32 v169, 0
	v_mov_b32_e32 v170, 0
	v_mov_b32_e32 v171, 0
	v_mov_b32_e32 v116, 0
	v_mov_b32_e32 v117, 0
	v_mov_b32_e32 v118, 0
	v_mov_b32_e32 v119, 0
	v_mov_b32_e32 v112, 0
	v_mov_b32_e32 v113, 0
	v_mov_b32_e32 v114, 0
	v_mov_b32_e32 v115, 0
	v_mov_b32_e32 v108, 0
	v_mov_b32_e32 v109, 0
	v_mov_b32_e32 v110, 0
	v_mov_b32_e32 v111, 0
	v_mov_b32_e32 v104, 0
	v_mov_b32_e32 v105, 0
	v_mov_b32_e32 v106, 0
	v_mov_b32_e32 v107, 0
	v_mov_b32_e32 v100, 0
	v_mov_b32_e32 v101, 0
	v_mov_b32_e32 v102, 0
	v_mov_b32_e32 v103, 0
	v_mov_b32_e32 v96, 0
	v_mov_b32_e32 v97, 0
	v_mov_b32_e32 v98, 0
	v_mov_b32_e32 v99, 0
	v_mov_b32_e32 v92, 0
	v_mov_b32_e32 v93, 0
	v_mov_b32_e32 v94, 0
	v_mov_b32_e32 v95, 0
	v_mov_b32_e32 v88, 0
	v_mov_b32_e32 v89, 0
	v_mov_b32_e32 v90, 0
	v_mov_b32_e32 v91, 0
	v_mov_b32_e32 v84, 0
	v_mov_b32_e32 v85, 0
	v_mov_b32_e32 v86, 0
	v_mov_b32_e32 v87, 0
	v_mov_b32_e32 v80, 0
	v_mov_b32_e32 v81, 0
	v_mov_b32_e32 v82, 0
	v_mov_b32_e32 v83, 0
	v_mov_b32_e32 v76, 0
	v_mov_b32_e32 v77, 0
	v_mov_b32_e32 v78, 0
	v_mov_b32_e32 v79, 0
	v_mov_b32_e32 v72, 0
	v_mov_b32_e32 v73, 0
	v_mov_b32_e32 v74, 0
	v_mov_b32_e32 v75, 0
	v_mov_b32_e32 v68, 0
	v_mov_b32_e32 v69, 0
	v_mov_b32_e32 v70, 0
	v_mov_b32_e32 v71, 0
	v_mov_b32_e32 v64, 0
	v_mov_b32_e32 v65, 0
	v_mov_b32_e32 v66, 0
	v_mov_b32_e32 v67, 0
	v_mov_b32_e32 v60, 0
	v_mov_b32_e32 v61, 0
	v_mov_b32_e32 v62, 0
	v_mov_b32_e32 v63, 0
	v_mov_b32_e32 v56, 0
	v_mov_b32_e32 v57, 0
	v_mov_b32_e32 v58, 0
	v_mov_b32_e32 v59, 0
	v_mov_b32_e32 v52, 0
	v_mov_b32_e32 v53, 0
	v_mov_b32_e32 v54, 0
	v_mov_b32_e32 v55, 0
	v_mov_b32_e32 v48, 0
	v_mov_b32_e32 v49, 0
	v_mov_b32_e32 v50, 0
	v_mov_b32_e32 v51, 0
	v_mov_b32_e32 v44, 0
	v_mov_b32_e32 v45, 0
	v_mov_b32_e32 v46, 0
	v_mov_b32_e32 v47, 0
	v_mov_b32_e32 v40, 0
	v_mov_b32_e32 v41, 0
	v_mov_b32_e32 v42, 0
	v_mov_b32_e32 v43, 0
	v_mov_b32_e32 v36, 0
	v_mov_b32_e32 v37, 0
	v_mov_b32_e32 v38, 0
	v_mov_b32_e32 v39, 0
	v_mov_b32_e32 v32, 0
	v_mov_b32_e32 v33, 0
	v_mov_b32_e32 v34, 0
	v_mov_b32_e32 v35, 0
	v_mov_b32_e32 v28, 0
	v_mov_b32_e32 v29, 0
	v_mov_b32_e32 v30, 0
	v_mov_b32_e32 v31, 0
	v_mov_b32_e32 v24, 0
	v_mov_b32_e32 v25, 0
	v_mov_b32_e32 v26, 0
	v_mov_b32_e32 v27, 0
	v_mov_b32_e32 v20, 0
	v_mov_b32_e32 v21, 0
	v_mov_b32_e32 v22, 0
	v_mov_b32_e32 v23, 0
	v_mov_b32_e32 v16, 0
	v_mov_b32_e32 v17, 0
	v_mov_b32_e32 v18, 0
	v_mov_b32_e32 v19, 0
	v_mov_b32_e32 v12, 0
	v_mov_b32_e32 v13, 0
	v_mov_b32_e32 v14, 0
	v_mov_b32_e32 v15, 0
	v_mov_b32_e32 v8, 0
	v_mov_b32_e32 v9, 0
	v_mov_b32_e32 v10, 0
	v_mov_b32_e32 v11, 0
	v_mov_b32_e32 v4, 0
	v_mov_b32_e32 v5, 0
	v_mov_b32_e32 v6, 0
	v_mov_b32_e32 v7, 0
	v_mov_b32_e32 v0, 0
	v_mov_b32_e32 v1, 0
	v_mov_b32_e32 v2, 0
	v_mov_b32_e32 v3, 0
	s_waitcnt vmcnt(6)
	s_barrier
	ds_read_b128 v[120:123], v209 offset:0
	ds_read_b128 v[124:127], v209 offset:1024
	ds_read_b128 v[128:131], v209 offset:2048
	ds_read_b128 v[132:135], v209 offset:3072
	ds_read_b128 v[152:155], v210 offset:8192
	ds_read_b128 v[156:159], v210 offset:9216
	ds_read_b128 v[160:163], v210 offset:10240
	ds_read_b128 v[164:167], v210 offset:11264
	ds_read_b128 v[176:179], v210 offset:12288
	ds_read_b128 v[180:183], v210 offset:13312
	s_add_u32 m0, s11, 0xc000
	s_nop 0
	global_load_lds_dwordx4 v203, s[2:3]
	s_add_u32 m0, s11, 0xc400
	s_nop 0
	global_load_lds_dwordx4 v204, s[2:3]
	s_add_u32 m0, s12, 0xe000
	s_nop 0
	global_load_lds_dwordx4 v205, s[4:5]
	s_add_u32 m0, s12, 0xe400
	s_nop 0
	global_load_lds_dwordx4 v206, s[4:5]
	s_add_u32 m0, s12, 0xe800
	s_nop 0
	global_load_lds_dwordx4 v207, s[4:5]
	s_add_u32 m0, s12, 0xec00
	s_nop 0
	global_load_lds_dwordx4 v208, s[4:5]
	s_add_u32 s2, s2, 0x40
	s_addc_u32 s3, s3, 0
	s_add_u32 s4, s4, 0x40
	s_addc_u32 s5, s5, 0
	ds_read_b128 v[184:187], v210 offset:14336
	ds_read_b128 v[188:191], v210 offset:15360
	s_waitcnt lgkmcnt(7)
	v_mfma_f32_16x16x32_bf16 v[172:175], v[152:155], v[120:123], v[172:175]
	v_mfma_f32_16x16x32_bf16 v[92:95], v[152:155], v[124:127], v[92:95]
	v_mfma_f32_16x16x32_bf16 v[60:63], v[152:155], v[128:131], v[60:63]
	v_mfma_f32_16x16x32_bf16 v[28:31], v[152:155], v[132:135], v[28:31]
	s_waitcnt lgkmcnt(6)
	v_mfma_f32_16x16x32_bf16 v[168:171], v[156:159], v[120:123], v[168:171]
	v_mfma_f32_16x16x32_bf16 v[88:91], v[156:159], v[124:127], v[88:91]
	v_mfma_f32_16x16x32_bf16 v[56:59], v[156:159], v[128:131], v[56:59]
	v_mfma_f32_16x16x32_bf16 v[24:27], v[156:159], v[132:135], v[24:27]
	s_waitcnt lgkmcnt(5)
	v_mfma_f32_16x16x32_bf16 v[116:119], v[160:163], v[120:123], v[116:119]
	v_mfma_f32_16x16x32_bf16 v[84:87], v[160:163], v[124:127], v[84:87]
	v_mfma_f32_16x16x32_bf16 v[52:55], v[160:163], v[128:131], v[52:55]
	v_mfma_f32_16x16x32_bf16 v[20:23], v[160:163], v[132:135], v[20:23]
	s_waitcnt lgkmcnt(4)
	v_mfma_f32_16x16x32_bf16 v[112:115], v[164:167], v[120:123], v[112:115]
	v_mfma_f32_16x16x32_bf16 v[80:83], v[164:167], v[124:127], v[80:83]
	v_mfma_f32_16x16x32_bf16 v[48:51], v[164:167], v[128:131], v[48:51]
	v_mfma_f32_16x16x32_bf16 v[16:19], v[164:167], v[132:135], v[16:19]
	s_waitcnt lgkmcnt(3)
	v_mfma_f32_16x16x32_bf16 v[108:111], v[176:179], v[120:123], v[108:111]
	v_mfma_f32_16x16x32_bf16 v[76:79], v[176:179], v[124:127], v[76:79]
	v_mfma_f32_16x16x32_bf16 v[44:47], v[176:179], v[128:131], v[44:47]
	v_mfma_f32_16x16x32_bf16 v[12:15], v[176:179], v[132:135], v[12:15]
	s_waitcnt lgkmcnt(2)
	v_mfma_f32_16x16x32_bf16 v[104:107], v[180:183], v[120:123], v[104:107]
	v_mfma_f32_16x16x32_bf16 v[72:75], v[180:183], v[124:127], v[72:75]
	v_mfma_f32_16x16x32_bf16 v[40:43], v[180:183], v[128:131], v[40:43]
	v_mfma_f32_16x16x32_bf16 v[8:11], v[180:183], v[132:135], v[8:11]
	s_waitcnt lgkmcnt(0)
	s_mov_b32 s13, 5
.Lg1_loop:
	s_waitcnt vmcnt(6)
	s_barrier
	ds_read_b128 v[136:139], v209 offset:24576
	ds_read_b128 v[140:143], v209 offset:25600
	ds_read_b128 v[144:147], v209 offset:26624
	ds_read_b128 v[148:151], v209 offset:27648
	ds_read_b128 v[152:155], v210 offset:32768
	ds_read_b128 v[156:159], v210 offset:33792
	ds_read_b128 v[160:163], v210 offset:34816
	ds_read_b128 v[164:167], v210 offset:35840
	ds_read_b128 v[176:179], v210 offset:36864
	ds_read_b128 v[180:183], v210 offset:37888
	v_mfma_f32_16x16x32_bf16 v[100:103], v[184:187], v[120:123], v[100:103]
	s_add_u32 m0, s11, 0x0
	v_mfma_f32_16x16x32_bf16 v[68:71], v[184:187], v[124:127], v[68:71]
	global_load_lds_dwordx4 v203, s[2:3]
	s_add_u32 m0, s11, 0x400
	v_mfma_f32_16x16x32_bf16 v[36:39], v[184:187], v[128:131], v[36:39]
	global_load_lds_dwordx4 v204, s[2:3]
	s_add_u32 m0, s12, 0x2000
	v_mfma_f32_16x16x32_bf16 v[4:7], v[184:187], v[132:135], v[4:7]
	global_load_lds_dwordx4 v205, s[4:5]
	s_add_u32 m0, s12, 0x2400
	v_mfma_f32_16x16x32_bf16 v[96:99], v[188:191], v[120:123], v[96:99]
	global_load_lds_dwordx4 v206, s[4:5]
	s_add_u32 m0, s12, 0x2800
	v_mfma_f32_16x16x32_bf16 v[64:67], v[188:191], v[124:127], v[64:67]
	global_load_lds_dwordx4 v207, s[4:5]
	s_add_u32 m0, s12, 0x2c00
	v_mfma_f32_16x16x32_bf16 v[32:35], v[188:191], v[128:131], v[32:35]
	global_load_lds_dwordx4 v208, s[4:5]
	v_mfma_f32_16x16x32_bf16 v[0:3], v[188:191], v[132:135], v[0:3]
	s_add_u32 s2, s2, 0x40
	s_addc_u32 s3, s3, 0
	s_add_u32 s4, s4, 0x40
	s_addc_u32 s5, s5, 0
	ds_read_b128 v[184:187], v210 offset:38912
	ds_read_b128 v[188:191], v210 offset:39936
	s_waitcnt lgkmcnt(7)
	v_mfma_f32_16x16x32_bf16 v[172:175], v[152:155], v[136:139], v[172:175]
	v_mfma_f32_16x16x32_bf16 v[92:95], v[152:155], v[140:143], v[92:95]
	v_mfma_f32_16x16x32_bf16 v[60:63], v[152:155], v[144:147], v[60:63]
	v_mfma_f32_16x16x32_bf16 v[28:31], v[152:155], v[148:151], v[28:31]
	s_waitcnt lgkmcnt(6)
	v_mfma_f32_16x16x32_bf16 v[168:171], v[156:159], v[136:139], v[168:171]
	v_mfma_f32_16x16x32_bf16 v[88:91], v[156:159], v[140:143], v[88:91]
	v_mfma_f32_16x16x32_bf16 v[56:59], v[156:159], v[144:147], v[56:59]
	v_mfma_f32_16x16x32_bf16 v[24:27], v[156:159], v[148:151], v[24:27]
	s_waitcnt lgkmcnt(5)
	v_mfma_f32_16x16x32_bf16 v[116:119], v[160:163], v[136:139], v[116:119]
	v_mfma_f32_16x16x32_bf16 v[84:87], v[160:163], v[140:143], v[84:87]
	v_mfma_f32_16x16x32_bf16 v[52:55], v[160:163], v[144:147], v[52:55]
	v_mfma_f32_16x16x32_bf16 v[20:23], v[160:163], v[148:151], v[20:23]
	s_waitcnt lgkmcnt(4)
	v_mfma_f32_16x16x32_bf16 v[112:115], v[164:167], v[136:139], v[112:115]
	v_mfma_f32_16x16x32_bf16 v[80:83], v[164:167], v[140:143], v[80:83]
	v_mfma_f32_16x16x32_bf16 v[48:51], v[164:167], v[144:147], v[48:51]
	v_mfma_f32_16x16x32_bf16 v[16:19], v[164:167], v[148:151], v[16:19]
	s_waitcnt lgkmcnt(3)
	v_mfma_f32_16x16x32_bf16 v[108:111], v[176:179], v[136:139], v[108:111]
	v_mfma_f32_16x16x32_bf16 v[76:79], v[176:179], v[140:143], v[76:79]
	v_mfma_f32_16x16x32_bf16 v[44:47], v[176:179], v[144:147], v[44:47]
	v_mfma_f32_16x16x32_bf16 v[12:15], v[176:179], v[148:151], v[12:15]
	s_waitcnt lgkmcnt(2)
	v_mfma_f32_16x16x32_bf16 v[104:107], v[180:183], v[136:139], v[104:107]
	v_mfma_f32_16x16x32_bf16 v[72:75], v[180:183], v[140:143], v[72:75]
	v_mfma_f32_16x16x32_bf16 v[40:43], v[180:183], v[144:147], v[40:43]
	v_mfma_f32_16x16x32_bf16 v[8:11], v[180:183], v[148:151], v[8:11]
	s_waitcnt lgkmcnt(0)
	s_waitcnt vmcnt(6)
	s_barrier
	ds_read_b128 v[120:123], v209 offset:49152
	ds_read_b128 v[124:127], v209 offset:50176
	ds_read_b128 v[128:131], v209 offset:51200
	ds_read_b128 v[132:135], v209 offset:52224
	ds_read_b128 v[152:155], v210 offset:57344
	ds_read_b128 v[156:159], v210 offset:58368
	ds_read_b128 v[160:163], v210 offset:59392
	ds_read_b128 v[164:167], v210 offset:60416
	ds_read_b128 v[176:179], v210 offset:61440
	ds_read_b128 v[180:183], v210 offset:62464
	v_mfma_f32_16x16x32_bf16 v[100:103], v[184:187], v[136:139], v[100:103]
	s_add_u32 m0, s11, 0x6000
	v_mfma_f32_16x16x32_bf16 v[68:71], v[184:187], v[140:143], v[68:71]
	global_load_lds_dwordx4 v203, s[2:3]
	s_add_u32 m0, s11, 0x6400
	v_mfma_f32_16x16x32_bf16 v[36:39], v[184:187], v[144:147], v[36:39]
	global_load_lds_dwordx4 v204, s[2:3]
	s_add_u32 m0, s12, 0x8000
	v_mfma_f32_16x16x32_bf16 v[4:7], v[184:187], v[148:151], v[4:7]
	global_load_lds_dwordx4 v205, s[4:5]
	s_add_u32 m0, s12, 0x8400
	v_mfma_f32_16x16x32_bf16 v[96:99], v[188:191], v[136:139], v[96:99]
	global_load_lds_dwordx4 v206, s[4:5]
	s_add_u32 m0, s12, 0x8800
	v_mfma_f32_16x16x32_bf16 v[64:67], v[188:191], v[140:143], v[64:67]
	global_load_lds_dwordx4 v207, s[4:5]
	s_add_u32 m0, s12, 0x8c00
	v_mfma_f32_16x16x32_bf16 v[32:35], v[188:191], v[144:147], v[32:35]
	global_load_lds_dwordx4 v208, s[4:5]
	v_mfma_f32_16x16x32_bf16 v[0:3], v[188:191], v[148:151], v[0:3]
	s_add_u32 s2, s2, 0x40
	s_addc_u32 s3, s3, 0
	s_add_u32 s4, s4, 0x40
	s_addc_u32 s5, s5, 0
	ds_read_b128 v[184:187], v210 offset:63488
	ds_read_b128 v[188:191], v210 offset:64512
	s_waitcnt lgkmcnt(7)
	v_mfma_f32_16x16x32_bf16 v[172:175], v[152:155], v[120:123], v[172:175]
	v_mfma_f32_16x16x32_bf16 v[92:95], v[152:155], v[124:127], v[92:95]
	v_mfma_f32_16x16x32_bf16 v[60:63], v[152:155], v[128:131], v[60:63]
	v_mfma_f32_16x16x32_bf16 v[28:31], v[152:155], v[132:135], v[28:31]
	s_waitcnt lgkmcnt(6)
	v_mfma_f32_16x16x32_bf16 v[168:171], v[156:159], v[120:123], v[168:171]
	v_mfma_f32_16x16x32_bf16 v[88:91], v[156:159], v[124:127], v[88:91]
	v_mfma_f32_16x16x32_bf16 v[56:59], v[156:159], v[128:131], v[56:59]
	v_mfma_f32_16x16x32_bf16 v[24:27], v[156:159], v[132:135], v[24:27]
	s_waitcnt lgkmcnt(5)
	v_mfma_f32_16x16x32_bf16 v[116:119], v[160:163], v[120:123], v[116:119]
	v_mfma_f32_16x16x32_bf16 v[84:87], v[160:163], v[124:127], v[84:87]
	v_mfma_f32_16x16x32_bf16 v[52:55], v[160:163], v[128:131], v[52:55]
	v_mfma_f32_16x16x32_bf16 v[20:23], v[160:163], v[132:135], v[20:23]
	s_waitcnt lgkmcnt(4)
	v_mfma_f32_16x16x32_bf16 v[112:115], v[164:167], v[120:123], v[112:115]
	v_mfma_f32_16x16x32_bf16 v[80:83], v[164:167], v[124:127], v[80:83]
	v_mfma_f32_16x16x32_bf16 v[48:51], v[164:167], v[128:131], v[48:51]
	v_mfma_f32_16x16x32_bf16 v[16:19], v[164:167], v[132:135], v[16:19]
	s_waitcnt lgkmcnt(3)
	v_mfma_f32_16x16x32_bf16 v[108:111], v[176:179], v[120:123], v[108:111]
	v_mfma_f32_16x16x32_bf16 v[76:79], v[176:179], v[124:127], v[76:79]
	v_mfma_f32_16x16x32_bf16 v[44:47], v[176:179], v[128:131], v[44:47]
	v_mfma_f32_16x16x32_bf16 v[12:15], v[176:179], v[132:135], v[12:15]
	s_waitcnt lgkmcnt(2)
	v_mfma_f32_16x16x32_bf16 v[104:107], v[180:183], v[120:123], v[104:107]
	v_mfma_f32_16x16x32_bf16 v[72:75], v[180:183], v[124:127], v[72:75]
	v_mfma_f32_16x16x32_bf16 v[40:43], v[180:183], v[128:131], v[40:43]
	v_mfma_f32_16x16x32_bf16 v[8:11], v[180:183], v[132:135], v[8:11]
	s_waitcnt lgkmcnt(0)
	s_waitcnt vmcnt(6)
	s_barrier
	ds_read_b128 v[136:139], v209 offset:0
	ds_read_b128 v[140:143], v209 offset:1024
	ds_read_b128 v[144:147], v209 offset:2048
	ds_read_b128 v[148:151], v209 offset:3072
	ds_read_b128 v[152:155], v210 offset:8192
	ds_read_b128 v[156:159], v210 offset:9216
	ds_read_b128 v[160:163], v210 offset:10240
	ds_read_b128 v[164:167], v210 offset:11264
	ds_read_b128 v[176:179], v210 offset:12288
	ds_read_b128 v[180:183], v210 offset:13312
	v_mfma_f32_16x16x32_bf16 v[100:103], v[184:187], v[120:123], v[100:103]
	s_add_u32 m0, s11, 0xc000
	v_mfma_f32_16x16x32_bf16 v[68:71], v[184:187], v[124:127], v[68:71]
	global_load_lds_dwordx4 v203, s[2:3]
	s_add_u32 m0, s11, 0xc400
	v_mfma_f32_16x16x32_bf16 v[36:39], v[184:187], v[128:131], v[36:39]
	global_load_lds_dwordx4 v204, s[2:3]
	s_add_u32 m0, s12, 0xe000
	v_mfma_f32_16x16x32_bf16 v[4:7], v[184:187], v[132:135], v[4:7]
	global_load_lds_dwordx4 v205, s[4:5]
	s_add_u32 m0, s12, 0xe400
	v_mfma_f32_16x16x32_bf16 v[96:99], v[188:191], v[120:123], v[96:99]
	global_load_lds_dwordx4 v206, s[4:5]
	s_add_u32 m0, s12, 0xe800
	v_mfma_f32_16x16x32_bf16 v[64:67], v[188:191], v[124:127], v[64:67]
	global_load_lds_dwordx4 v207, s[4:5]
	s_add_u32 m0, s12, 0xec00
	v_mfma_f32_16x16x32_bf16 v[32:35], v[188:191], v[128:131], v[32:35]
	global_load_lds_dwordx4 v208, s[4:5]
	v_mfma_f32_16x16x32_bf16 v[0:3], v[188:191], v[132:135], v[0:3]
	s_add_u32 s2, s2, 0x40
	s_addc_u32 s3, s3, 0
	s_add_u32 s4, s4, 0x40
	s_addc_u32 s5, s5, 0
	ds_read_b128 v[184:187], v210 offset:14336
	ds_read_b128 v[188:191], v210 offset:15360
	s_waitcnt lgkmcnt(7)
	v_mfma_f32_16x16x32_bf16 v[172:175], v[152:155], v[136:139], v[172:175]
	v_mfma_f32_16x16x32_bf16 v[92:95], v[152:155], v[140:143], v[92:95]
	v_mfma_f32_16x16x32_bf16 v[60:63], v[152:155], v[144:147], v[60:63]
	v_mfma_f32_16x16x32_bf16 v[28:31], v[152:155], v[148:151], v[28:31]
	s_waitcnt lgkmcnt(6)
	v_mfma_f32_16x16x32_bf16 v[168:171], v[156:159], v[136:139], v[168:171]
	v_mfma_f32_16x16x32_bf16 v[88:91], v[156:159], v[140:143], v[88:91]
	v_mfma_f32_16x16x32_bf16 v[56:59], v[156:159], v[144:147], v[56:59]
	v_mfma_f32_16x16x32_bf16 v[24:27], v[156:159], v[148:151], v[24:27]
	s_waitcnt lgkmcnt(5)
	v_mfma_f32_16x16x32_bf16 v[116:119], v[160:163], v[136:139], v[116:119]
	v_mfma_f32_16x16x32_bf16 v[84:87], v[160:163], v[140:143], v[84:87]
	v_mfma_f32_16x16x32_bf16 v[52:55], v[160:163], v[144:147], v[52:55]
	v_mfma_f32_16x16x32_bf16 v[20:23], v[160:163], v[148:151], v[20:23]
	s_waitcnt lgkmcnt(4)
	v_mfma_f32_16x16x32_bf16 v[112:115], v[164:167], v[136:139], v[112:115]
	v_mfma_f32_16x16x32_bf16 v[80:83], v[164:167], v[140:143], v[80:83]
	v_mfma_f32_16x16x32_bf16 v[48:51], v[164:167], v[144:147], v[48:51]
	v_mfma_f32_16x16x32_bf16 v[16:19], v[164:167], v[148:151], v[16:19]
	s_waitcnt lgkmcnt(3)
	v_mfma_f32_16x16x32_bf16 v[108:111], v[176:179], v[136:139], v[108:111]
	v_mfma_f32_16x16x32_bf16 v[76:79], v[176:179], v[140:143], v[76:79]
	v_mfma_f32_16x16x32_bf16 v[44:47], v[176:179], v[144:147], v[44:47]
	v_mfma_f32_16x16x32_bf16 v[12:15], v[176:179], v[148:151], v[12:15]
	s_waitcnt lgkmcnt(2)
	v_mfma_f32_16x16x32_bf16 v[104:107], v[180:183], v[136:139], v[104:107]
	v_mfma_f32_16x16x32_bf16 v[72:75], v[180:183], v[140:143], v[72:75]
	v_mfma_f32_16x16x32_bf16 v[40:43], v[180:183], v[144:147], v[40:43]
	v_mfma_f32_16x16x32_bf16 v[8:11], v[180:183], v[148:151], v[8:11]
	s_waitcnt lgkmcnt(0)
	s_waitcnt vmcnt(6)
	s_barrier
	ds_read_b128 v[120:123], v209 offset:24576
	ds_read_b128 v[124:127], v209 offset:25600
	ds_read_b128 v[128:131], v209 offset:26624
	ds_read_b128 v[132:135], v209 offset:27648
	ds_read_b128 v[152:155], v210 offset:32768
	ds_read_b128 v[156:159], v210 offset:33792
	ds_read_b128 v[160:163], v210 offset:34816
	ds_read_b128 v[164:167], v210 offset:35840
	ds_read_b128 v[176:179], v210 offset:36864
	ds_read_b128 v[180:183], v210 offset:37888
	v_mfma_f32_16x16x32_bf16 v[100:103], v[184:187], v[136:139], v[100:103]
	s_add_u32 m0, s11, 0x0
	v_mfma_f32_16x16x32_bf16 v[68:71], v[184:187], v[140:143], v[68:71]
	global_load_lds_dwordx4 v203, s[2:3]
	s_add_u32 m0, s11, 0x400
	v_mfma_f32_16x16x32_bf16 v[36:39], v[184:187], v[144:147], v[36:39]
	global_load_lds_dwordx4 v204, s[2:3]
	s_add_u32 m0, s12, 0x2000
	v_mfma_f32_16x16x32_bf16 v[4:7], v[184:187], v[148:151], v[4:7]
	global_load_lds_dwordx4 v205, s[4:5]
	s_add_u32 m0, s12, 0x2400
	v_mfma_f32_16x16x32_bf16 v[96:99], v[188:191], v[136:139], v[96:99]
	global_load_lds_dwordx4 v206, s[4:5]
	s_add_u32 m0, s12, 0x2800
	v_mfma_f32_16x16x32_bf16 v[64:67], v[188:191], v[140:143], v[64:67]
	global_load_lds_dwordx4 v207, s[4:5]
	s_add_u32 m0, s12, 0x2c00
	v_mfma_f32_16x16x32_bf16 v[32:35], v[188:191], v[144:147], v[32:35]
	global_load_lds_dwordx4 v208, s[4:5]
	v_mfma_f32_16x16x32_bf16 v[0:3], v[188:191], v[148:151], v[0:3]
	s_add_u32 s2, s2, 0x40
	s_addc_u32 s3, s3, 0
	s_add_u32 s4, s4, 0x40
	s_addc_u32 s5, s5, 0
	ds_read_b128 v[184:187], v210 offset:38912
	ds_read_b128 v[188:191], v210 offset:39936
	s_waitcnt lgkmcnt(7)
	v_mfma_f32_16x16x32_bf16 v[172:175], v[152:155], v[120:123], v[172:175]
	v_mfma_f32_16x16x32_bf16 v[92:95], v[152:155], v[124:127], v[92:95]
	v_mfma_f32_16x16x32_bf16 v[60:63], v[152:155], v[128:131], v[60:63]
	v_mfma_f32_16x16x32_bf16 v[28:31], v[152:155], v[132:135], v[28:31]
	s_waitcnt lgkmcnt(6)
	v_mfma_f32_16x16x32_bf16 v[168:171], v[156:159], v[120:123], v[168:171]
	v_mfma_f32_16x16x32_bf16 v[88:91], v[156:159], v[124:127], v[88:91]
	v_mfma_f32_16x16x32_bf16 v[56:59], v[156:159], v[128:131], v[56:59]
	v_mfma_f32_16x16x32_bf16 v[24:27], v[156:159], v[132:135], v[24:27]
	s_waitcnt lgkmcnt(5)
	v_mfma_f32_16x16x32_bf16 v[116:119], v[160:163], v[120:123], v[116:119]
	v_mfma_f32_16x16x32_bf16 v[84:87], v[160:163], v[124:127], v[84:87]
	v_mfma_f32_16x16x32_bf16 v[52:55], v[160:163], v[128:131], v[52:55]
	v_mfma_f32_16x16x32_bf16 v[20:23], v[160:163], v[132:135], v[20:23]
	s_waitcnt lgkmcnt(4)
	v_mfma_f32_16x16x32_bf16 v[112:115], v[164:167], v[120:123], v[112:115]
	v_mfma_f32_16x16x32_bf16 v[80:83], v[164:167], v[124:127], v[80:83]
	v_mfma_f32_16x16x32_bf16 v[48:51], v[164:167], v[128:131], v[48:51]
	v_mfma_f32_16x16x32_bf16 v[16:19], v[164:167], v[132:135], v[16:19]
	s_waitcnt lgkmcnt(3)
	v_mfma_f32_16x16x32_bf16 v[108:111], v[176:179], v[120:123], v[108:111]
	v_mfma_f32_16x16x32_bf16 v[76:79], v[176:179], v[124:127], v[76:79]
	v_mfma_f32_16x16x32_bf16 v[44:47], v[176:179], v[128:131], v[44:47]
	v_mfma_f32_16x16x32_bf16 v[12:15], v[176:179], v[132:135], v[12:15]
	s_waitcnt lgkmcnt(2)
	v_mfma_f32_16x16x32_bf16 v[104:107], v[180:183], v[120:123], v[104:107]
	v_mfma_f32_16x16x32_bf16 v[72:75], v[180:183], v[124:127], v[72:75]
	v_mfma_f32_16x16x32_bf16 v[40:43], v[180:183], v[128:131], v[40:43]
	v_mfma_f32_16x16x32_bf16 v[8:11], v[180:183], v[132:135], v[8:11]
	s_waitcnt lgkmcnt(0)
	s_waitcnt vmcnt(6)
	s_barrier
	ds_read_b128 v[136:139], v209 offset:49152
	ds_read_b128 v[140:143], v209 offset:50176
	ds_read_b128 v[144:147], v209 offset:51200
	ds_read_b128 v[148:151], v209 offset:52224
	ds_read_b128 v[152:155], v210 offset:57344
	ds_read_b128 v[156:159], v210 offset:58368
	ds_read_b128 v[160:163], v210 offset:59392
	ds_read_b128 v[164:167], v210 offset:60416
	ds_read_b128 v[176:179], v210 offset:61440
	ds_read_b128 v[180:183], v210 offset:62464
	v_mfma_f32_16x16x32_bf16 v[100:103], v[184:187], v[120:123], v[100:103]
	s_add_u32 m0, s11, 0x6000
	v_mfma_f32_16x16x32_bf16 v[68:71], v[184:187], v[124:127], v[68:71]
	global_load_lds_dwordx4 v203, s[2:3]
	s_add_u32 m0, s11, 0x6400
	v_mfma_f32_16x16x32_bf16 v[36:39], v[184:187], v[128:131], v[36:39]
	global_load_lds_dwordx4 v204, s[2:3]
	s_add_u32 m0, s12, 0x8000
	v_mfma_f32_16x16x32_bf16 v[4:7], v[184:187], v[132:135], v[4:7]
	global_load_lds_dwordx4 v205, s[4:5]
	s_add_u32 m0, s12, 0x8400
	v_mfma_f32_16x16x32_bf16 v[96:99], v[188:191], v[120:123], v[96:99]
	global_load_lds_dwordx4 v206, s[4:5]
	s_add_u32 m0, s12, 0x8800
	v_mfma_f32_16x16x32_bf16 v[64:67], v[188:191], v[124:127], v[64:67]
	global_load_lds_dwordx4 v207, s[4:5]
	s_add_u32 m0, s12, 0x8c00
	v_mfma_f32_16x16x32_bf16 v[32:35], v[188:191], v[128:131], v[32:35]
	global_load_lds_dwordx4 v208, s[4:5]
	v_mfma_f32_16x16x32_bf16 v[0:3], v[188:191], v[132:135], v[0:3]
	s_add_u32 s2, s2, 0x40
	s_addc_u32 s3, s3, 0
	s_add_u32 s4, s4, 0x40
	s_addc_u32 s5, s5, 0
	ds_read_b128 v[184:187], v210 offset:63488
	ds_read_b128 v[188:191], v210 offset:64512
	s_waitcnt lgkmcnt(7)
	v_mfma_f32_16x16x32_bf16 v[172:175], v[152:155], v[136:139], v[172:175]
	v_mfma_f32_16x16x32_bf16 v[92:95], v[152:155], v[140:143], v[92:95]
	v_mfma_f32_16x16x32_bf16 v[60:63], v[152:155], v[144:147], v[60:63]
	v_mfma_f32_16x16x32_bf16 v[28:31], v[152:155], v[148:151], v[28:31]
	s_waitcnt lgkmcnt(6)
	v_mfma_f32_16x16x32_bf16 v[168:171], v[156:159], v[136:139], v[168:171]
	v_mfma_f32_16x16x32_bf16 v[88:91], v[156:159], v[140:143], v[88:91]
	v_mfma_f32_16x16x32_bf16 v[56:59], v[156:159], v[144:147], v[56:59]
	v_mfma_f32_16x16x32_bf16 v[24:27], v[156:159], v[148:151], v[24:27]
	s_waitcnt lgkmcnt(5)
	v_mfma_f32_16x16x32_bf16 v[116:119], v[160:163], v[136:139], v[116:119]
	v_mfma_f32_16x16x32_bf16 v[84:87], v[160:163], v[140:143], v[84:87]
	v_mfma_f32_16x16x32_bf16 v[52:55], v[160:163], v[144:147], v[52:55]
	v_mfma_f32_16x16x32_bf16 v[20:23], v[160:163], v[148:151], v[20:23]
	s_waitcnt lgkmcnt(4)
	v_mfma_f32_16x16x32_bf16 v[112:115], v[164:167], v[136:139], v[112:115]
	v_mfma_f32_16x16x32_bf16 v[80:83], v[164:167], v[140:143], v[80:83]
	v_mfma_f32_16x16x32_bf16 v[48:51], v[164:167], v[144:147], v[48:51]
	v_mfma_f32_16x16x32_bf16 v[16:19], v[164:167], v[148:151], v[16:19]
	s_waitcnt lgkmcnt(3)
	v_mfma_f32_16x16x32_bf16 v[108:111], v[176:179], v[136:139], v[108:111]
	v_mfma_f32_16x16x32_bf16 v[76:79], v[176:179], v[140:143], v[76:79]
	v_mfma_f32_16x16x32_bf16 v[44:47], v[176:179], v[144:147], v[44:47]
	v_mfma_f32_16x16x32_bf16 v[12:15], v[176:179], v[148:151], v[12:15]
	s_waitcnt lgkmcnt(2)
	v_mfma_f32_16x16x32_bf16 v[104:107], v[180:183], v[136:139], v[104:107]
	v_mfma_f32_16x16x32_bf16 v[72:75], v[180:183], v[140:143], v[72:75]
	v_mfma_f32_16x16x32_bf16 v[40:43], v[180:183], v[144:147], v[40:43]
	v_mfma_f32_16x16x32_bf16 v[8:11], v[180:183], v[148:151], v[8:11]
	s_waitcnt lgkmcnt(0)
	s_waitcnt vmcnt(6)
	s_barrier
	ds_read_b128 v[120:123], v209 offset:0
	ds_read_b128 v[124:127], v209 offset:1024
	ds_read_b128 v[128:131], v209 offset:2048
	ds_read_b128 v[132:135], v209 offset:3072
	ds_read_b128 v[152:155], v210 offset:8192
	ds_read_b128 v[156:159], v210 offset:9216
	ds_read_b128 v[160:163], v210 offset:10240
	ds_read_b128 v[164:167], v210 offset:11264
	ds_read_b128 v[176:179], v210 offset:12288
	ds_read_b128 v[180:183], v210 offset:13312
	v_mfma_f32_16x16x32_bf16 v[100:103], v[184:187], v[136:139], v[100:103]
	s_add_u32 m0, s11, 0xc000
	v_mfma_f32_16x16x32_bf16 v[68:71], v[184:187], v[140:143], v[68:71]
	global_load_lds_dwordx4 v203, s[2:3]
	s_add_u32 m0, s11, 0xc400
	v_mfma_f32_16x16x32_bf16 v[36:39], v[184:187], v[144:147], v[36:39]
	global_load_lds_dwordx4 v204, s[2:3]
	s_add_u32 m0, s12, 0xe000
	v_mfma_f32_16x16x32_bf16 v[4:7], v[184:187], v[148:151], v[4:7]
	global_load_lds_dwordx4 v205, s[4:5]
	s_add_u32 m0, s12, 0xe400
	v_mfma_f32_16x16x32_bf16 v[96:99], v[188:191], v[136:139], v[96:99]
	global_load_lds_dwordx4 v206, s[4:5]
	s_add_u32 m0, s12, 0xe800
	v_mfma_f32_16x16x32_bf16 v[64:67], v[188:191], v[140:143], v[64:67]
	global_load_lds_dwordx4 v207, s[4:5]
	s_add_u32 m0, s12, 0xec00
	v_mfma_f32_16x16x32_bf16 v[32:35], v[188:191], v[144:147], v[32:35]
	global_load_lds_dwordx4 v208, s[4:5]
	v_mfma_f32_16x16x32_bf16 v[0:3], v[188:191], v[148:151], v[0:3]
	s_add_u32 s2, s2, 0x40
	s_addc_u32 s3, s3, 0
	s_add_u32 s4, s4, 0x40
	s_addc_u32 s5, s5, 0
	ds_read_b128 v[184:187], v210 offset:14336
	ds_read_b128 v[188:191], v210 offset:15360
	s_waitcnt lgkmcnt(7)
	v_mfma_f32_16x16x32_bf16 v[172:175], v[152:155], v[120:123], v[172:175]
	v_mfma_f32_16x16x32_bf16 v[92:95], v[152:155], v[124:127], v[92:95]
	v_mfma_f32_16x16x32_bf16 v[60:63], v[152:155], v[128:131], v[60:63]
	v_mfma_f32_16x16x32_bf16 v[28:31], v[152:155], v[132:135], v[28:31]
	s_waitcnt lgkmcnt(6)
	v_mfma_f32_16x16x32_bf16 v[168:171], v[156:159], v[120:123], v[168:171]
	v_mfma_f32_16x16x32_bf16 v[88:91], v[156:159], v[124:127], v[88:91]
	v_mfma_f32_16x16x32_bf16 v[56:59], v[156:159], v[128:131], v[56:59]
	v_mfma_f32_16x16x32_bf16 v[24:27], v[156:159], v[132:135], v[24:27]
	s_waitcnt lgkmcnt(5)
	v_mfma_f32_16x16x32_bf16 v[116:119], v[160:163], v[120:123], v[116:119]
	v_mfma_f32_16x16x32_bf16 v[84:87], v[160:163], v[124:127], v[84:87]
	v_mfma_f32_16x16x32_bf16 v[52:55], v[160:163], v[128:131], v[52:55]
	v_mfma_f32_16x16x32_bf16 v[20:23], v[160:163], v[132:135], v[20:23]
	s_waitcnt lgkmcnt(4)
	v_mfma_f32_16x16x32_bf16 v[112:115], v[164:167], v[120:123], v[112:115]
	v_mfma_f32_16x16x32_bf16 v[80:83], v[164:167], v[124:127], v[80:83]
	v_mfma_f32_16x16x32_bf16 v[48:51], v[164:167], v[128:131], v[48:51]
	v_mfma_f32_16x16x32_bf16 v[16:19], v[164:167], v[132:135], v[16:19]
	s_waitcnt lgkmcnt(3)
	v_mfma_f32_16x16x32_bf16 v[108:111], v[176:179], v[120:123], v[108:111]
	v_mfma_f32_16x16x32_bf16 v[76:79], v[176:179], v[124:127], v[76:79]
	v_mfma_f32_16x16x32_bf16 v[44:47], v[176:179], v[128:131], v[44:47]
	v_mfma_f32_16x16x32_bf16 v[12:15], v[176:179], v[132:135], v[12:15]
	s_waitcnt lgkmcnt(2)
	v_mfma_f32_16x16x32_bf16 v[104:107], v[180:183], v[120:123], v[104:107]
	v_mfma_f32_16x16x32_bf16 v[72:75], v[180:183], v[124:127], v[72:75]
	v_mfma_f32_16x16x32_bf16 v[40:43], v[180:183], v[128:131], v[40:43]
	v_mfma_f32_16x16x32_bf16 v[8:11], v[180:183], v[132:135], v[8:11]
	s_waitcnt lgkmcnt(0)
	s_sub_u32 s13, s13, 1
	s_cmp_lg_u32 s13, 0
	s_cbranch_scc1 .Lg1_loop
	s_waitcnt vmcnt(6)
	s_barrier
	ds_read_b128 v[136:139], v209 offset:24576
	ds_read_b128 v[140:143], v209 offset:25600
	ds_read_b128 v[144:147], v209 offset:26624
	ds_read_b128 v[148:151], v209 offset:27648
	ds_read_b128 v[152:155], v210 offset:32768
	ds_read_b128 v[156:159], v210 offset:33792
	ds_read_b128 v[160:163], v210 offset:34816
	ds_read_b128 v[164:167], v210 offset:35840
	ds_read_b128 v[176:179], v210 offset:36864
	ds_read_b128 v[180:183], v210 offset:37888
	v_mfma_f32_16x16x32_bf16 v[100:103], v[184:187], v[120:123], v[100:103]
	v_mfma_f32_16x16x32_bf16 v[68:71], v[184:187], v[124:127], v[68:71]
	v_mfma_f32_16x16x32_bf16 v[36:39], v[184:187], v[128:131], v[36:39]
	v_mfma_f32_16x16x32_bf16 v[4:7], v[184:187], v[132:135], v[4:7]
	v_mfma_f32_16x16x32_bf16 v[96:99], v[188:191], v[120:123], v[96:99]
	v_mfma_f32_16x16x32_bf16 v[64:67], v[188:191], v[124:127], v[64:67]
	v_mfma_f32_16x16x32_bf16 v[32:35], v[188:191], v[128:131], v[32:35]
	v_mfma_f32_16x16x32_bf16 v[0:3], v[188:191], v[132:135], v[0:3]
	ds_read_b128 v[184:187], v210 offset:38912
	ds_read_b128 v[188:191], v210 offset:39936
	s_waitcnt lgkmcnt(7)
	v_mfma_f32_16x16x32_bf16 v[172:175], v[152:155], v[136:139], v[172:175]
	v_mfma_f32_16x16x32_bf16 v[92:95], v[152:155], v[140:143], v[92:95]
	v_mfma_f32_16x16x32_bf16 v[60:63], v[152:155], v[144:147], v[60:63]
	v_mfma_f32_16x16x32_bf16 v[28:31], v[152:155], v[148:151], v[28:31]
	s_waitcnt lgkmcnt(6)
	v_mfma_f32_16x16x32_bf16 v[168:171], v[156:159], v[136:139], v[168:171]
	v_mfma_f32_16x16x32_bf16 v[88:91], v[156:159], v[140:143], v[88:91]
	v_mfma_f32_16x16x32_bf16 v[56:59], v[156:159], v[144:147], v[56:59]
	v_mfma_f32_16x16x32_bf16 v[24:27], v[156:159], v[148:151], v[24:27]
	s_waitcnt lgkmcnt(5)
	v_mfma_f32_16x16x32_bf16 v[116:119], v[160:163], v[136:139], v[116:119]
	v_mfma_f32_16x16x32_bf16 v[84:87], v[160:163], v[140:143], v[84:87]
	v_mfma_f32_16x16x32_bf16 v[52:55], v[160:163], v[144:147], v[52:55]
	v_mfma_f32_16x16x32_bf16 v[20:23], v[160:163], v[148:151], v[20:23]
	s_waitcnt lgkmcnt(4)
	v_mfma_f32_16x16x32_bf16 v[112:115], v[164:167], v[136:139], v[112:115]
	v_mfma_f32_16x16x32_bf16 v[80:83], v[164:167], v[140:143], v[80:83]
	v_mfma_f32_16x16x32_bf16 v[48:51], v[164:167], v[144:147], v[48:51]
	v_mfma_f32_16x16x32_bf16 v[16:19], v[164:167], v[148:151], v[16:19]
	s_waitcnt lgkmcnt(3)
	v_mfma_f32_16x16x32_bf16 v[108:111], v[176:179], v[136:139], v[108:111]
	v_mfma_f32_16x16x32_bf16 v[76:79], v[176:179], v[140:143], v[76:79]
	v_mfma_f32_16x16x32_bf16 v[44:47], v[176:179], v[144:147], v[44:47]
	v_mfma_f32_16x16x32_bf16 v[12:15], v[176:179], v[148:151], v[12:15]
	s_waitcnt lgkmcnt(2)
	v_mfma_f32_16x16x32_bf16 v[104:107], v[180:183], v[136:139], v[104:107]
	v_mfma_f32_16x16x32_bf16 v[72:75], v[180:183], v[140:143], v[72:75]
	v_mfma_f32_16x16x32_bf16 v[40:43], v[180:183], v[144:147], v[40:43]
	v_mfma_f32_16x16x32_bf16 v[8:11], v[180:183], v[148:151], v[8:11]
	s_waitcnt lgkmcnt(0)
	v_mfma_f32_16x16x32_bf16 v[100:103], v[184:187], v[136:139], v[100:103]
	v_mfma_f32_16x16x32_bf16 v[68:71], v[184:187], v[140:143], v[68:71]
	v_mfma_f32_16x16x32_bf16 v[36:39], v[184:187], v[144:147], v[36:39]
	v_mfma_f32_16x16x32_bf16 v[4:7], v[184:187], v[148:151], v[4:7]
	v_mfma_f32_16x16x32_bf16 v[96:99], v[188:191], v[136:139], v[96:99]
	v_mfma_f32_16x16x32_bf16 v[64:67], v[188:191], v[140:143], v[64:67]
	v_mfma_f32_16x16x32_bf16 v[32:35], v[188:191], v[144:147], v[32:35]
	v_mfma_f32_16x16x32_bf16 v[0:3], v[188:191], v[148:151], v[0:3]
	s_waitcnt vmcnt(0)
	s_nop 7
	s_nop 7
	s_branch .LBB0_89

.LBB0_509:
	s_andn2_b64 vcc, exec, s[2:3]
	s_cbranch_vccnz .LBB0_503
	v_readlane_b32 s11, v255, 8
	v_readlane_b32 s12, v255, 6
	v_readlane_b32 s2, v253, 4
	v_readlane_b32 s3, v253, 5
	s_lshl_b32 s13, s11, 18
	s_add_u32 s2, s2, s13
	s_addc_u32 s3, s3, 0
	s_lshl_b32 s13, s12, 19
	s_add_u32 s4, s50, 0x5510000
	s_addc_u32 s5, s51, 0
	s_add_u32 s4, s4, s13
	s_addc_u32 s5, s5, 0
	v_and_b32_e32 v92, 63, v216
	v_lshrrev_b32_e32 v93, 6, v216
	v_lshrrev_b32_e32 v94, 2, v92
	v_and_b32_e32 v95, 3, v92
	v_readfirstlane_b32 s11, v93
	v_lshrrev_b32_e32 v100, 3, v94
	v_mul_u32_u24_e32 v100, 3, v100
	v_xor_b32_e32 v100, v95, v100
	v_lshlrev_b32_e32 v100, 4, v100
	v_lshl_add_u32 v101, v93, 5, v94
	v_lshl_add_u32 v203, v101, 11, v100
	v_add_u32_e32 v204, 0x8000, v203
	v_lshl_add_u32 v101, v93, 6, v94
	v_lshl_add_u32 v205, v101, 11, v100
	v_add_u32_e32 v206, 0x8000, v205
	v_add_u32_e32 v207, 0x10000, v205
	v_add_u32_e32 v208, 0x18000, v205
	v_and_b32_e32 v102, 15, v92
	v_lshrrev_b32_e32 v103, 4, v92
	v_lshrrev_b32_e32 v108, 3, v102
	v_mul_u32_u24_e32 v108, 3, v108
	v_xor_b32_e32 v108, v103, v108
	v_lshlrev_b32_e32 v108, 4, v108
	v_lshl_add_u32 v108, v102, 6, v108
	v_lshrrev_b32_e32 v109, 1, v93
	v_and_b32_e32 v110, 1, v93
	v_lshl_add_u32 v209, v109, 12, v108
	v_lshl_add_u32 v210, v110, 13, v108
	s_lshl_b32 s12, s11, 12
	s_lshl_b32 s11, s11, 11
	s_add_u32 m0, s11, 0x0
	s_nop 0
	global_load_lds_dwordx4 v203, s[2:3]
	s_add_u32 m0, s11, 0x400
	s_nop 0
	global_load_lds_dwordx4 v204, s[2:3]
	s_add_u32 m0, s12, 0x2000
	s_nop 0
	global_load_lds_dwordx4 v205, s[4:5]
	s_add_u32 m0, s12, 0x2400
	s_nop 0
	global_load_lds_dwordx4 v206, s[4:5]
	s_add_u32 m0, s12, 0x2800
	s_nop 0
	global_load_lds_dwordx4 v207, s[4:5]
	s_add_u32 m0, s12, 0x2c00
	s_nop 0
	global_load_lds_dwordx4 v208, s[4:5]
	s_add_u32 s2, s2, 0x40
	s_addc_u32 s3, s3, 0
	s_add_u32 s4, s4, 0x40
	s_addc_u32 s5, s5, 0
	s_add_u32 m0, s11, 0x6000
	s_nop 0
	global_load_lds_dwordx4 v203, s[2:3]
	s_add_u32 m0, s11, 0x6400
	s_nop 0
	global_load_lds_dwordx4 v204, s[2:3]
	s_add_u32 m0, s12, 0x8000
	s_nop 0
	global_load_lds_dwordx4 v205, s[4:5]
	s_add_u32 m0, s12, 0x8400
	s_nop 0
	global_load_lds_dwordx4 v206, s[4:5]
	s_add_u32 m0, s12, 0x8800
	s_nop 0
	global_load_lds_dwordx4 v207, s[4:5]
	s_add_u32 m0, s12, 0x8c00
	s_nop 0
	global_load_lds_dwordx4 v208, s[4:5]
	s_add_u32 s2, s2, 0x40
	s_addc_u32 s3, s3, 0
	s_add_u32 s4, s4, 0x40
	s_addc_u32 s5, s5, 0
	v_mov_b32_e32 v156, 0
	v_mov_b32_e32 v157, 0
	v_mov_b32_e32 v158, 0
	v_mov_b32_e32 v159, 0
	v_mov_b32_e32 v152, 0
	v_mov_b32_e32 v153, 0
	v_mov_b32_e32 v154, 0
	v_mov_b32_e32 v155, 0
	v_mov_b32_e32 v148, 0
	v_mov_b32_e32 v149, 0
	v_mov_b32_e32 v150, 0
	v_mov_b32_e32 v151, 0
	v_mov_b32_e32 v144, 0
	v_mov_b32_e32 v145, 0
	v_mov_b32_e32 v146, 0
	v_mov_b32_e32 v147, 0
	v_mov_b32_e32 v172, 0
	v_mov_b32_e32 v173, 0
	v_mov_b32_e32 v174, 0
	v_mov_b32_e32 v175, 0
	v_mov_b32_e32 v168, 0
	v_mov_b32_e32 v169, 0
	v_mov_b32_e32 v170, 0
	v_mov_b32_e32 v171, 0
	v_mov_b32_e32 v164, 0
	v_mov_b32_e32 v165, 0
	v_mov_b32_e32 v166, 0
	v_mov_b32_e32 v167, 0
	v_mov_b32_e32 v160, 0
	v_mov_b32_e32 v161, 0
	v_mov_b32_e32 v162, 0
	v_mov_b32_e32 v163, 0
	v_mov_b32_e32 v124, 0
	v_mov_b32_e32 v125, 0
	v_mov_b32_e32 v126, 0
	v_mov_b32_e32 v127, 0
	v_mov_b32_e32 v120, 0
	v_mov_b32_e32 v121, 0
	v_mov_b32_e32 v122, 0
	v_mov_b32_e32 v123, 0
	v_mov_b32_e32 v112, 0
	v_mov_b32_e32 v113, 0
	v_mov_b32_e32 v114, 0
	v_mov_b32_e32 v115, 0
	v_mov_b32_e32 v104, 0
	v_mov_b32_e32 v105, 0
	v_mov_b32_e32 v106, 0
	v_mov_b32_e32 v107, 0
	v_mov_b32_e32 v140, 0
	v_mov_b32_e32 v141, 0
	v_mov_b32_e32 v142, 0
	v_mov_b32_e32 v143, 0
	v_mov_b32_e32 v136, 0
	v_mov_b32_e32 v137, 0
	v_mov_b32_e32 v138, 0
	v_mov_b32_e32 v139, 0
	v_mov_b32_e32 v132, 0
	v_mov_b32_e32 v133, 0
	v_mov_b32_e32 v134, 0
	v_mov_b32_e32 v135, 0
	v_mov_b32_e32 v128, 0
	v_mov_b32_e32 v129, 0
	v_mov_b32_e32 v130, 0
	v_mov_b32_e32 v131, 0
	v_mov_b32_e32 v52, 0
	v_mov_b32_e32 v53, 0
	v_mov_b32_e32 v54, 0
	v_mov_b32_e32 v55, 0
	v_mov_b32_e32 v40, 0
	v_mov_b32_e32 v41, 0
	v_mov_b32_e32 v42, 0
	v_mov_b32_e32 v43, 0
	v_mov_b32_e32 v36, 0
	v_mov_b32_e32 v37, 0
	v_mov_b32_e32 v38, 0
	v_mov_b32_e32 v39, 0
	v_mov_b32_e32 v32, 0
	v_mov_b32_e32 v33, 0
	v_mov_b32_e32 v34, 0
	v_mov_b32_e32 v35, 0
	v_mov_b32_e32 v96, 0
	v_mov_b32_e32 v97, 0
	v_mov_b32_e32 v98, 0
	v_mov_b32_e32 v99, 0
	v_mov_b32_e32 v88, 0
	v_mov_b32_e32 v89, 0
	v_mov_b32_e32 v90, 0
	v_mov_b32_e32 v91, 0
	v_mov_b32_e32 v76, 0
	v_mov_b32_e32 v77, 0
	v_mov_b32_e32 v78, 0
	v_mov_b32_e32 v79, 0
	v_mov_b32_e32 v68, 0
	v_mov_b32_e32 v69, 0
	v_mov_b32_e32 v70, 0
	v_mov_b32_e32 v71, 0
	v_mov_b32_e32 v12, 0
	v_mov_b32_e32 v13, 0
	v_mov_b32_e32 v14, 0
	v_mov_b32_e32 v15, 0
	v_mov_b32_e32 v8, 0
	v_mov_b32_e32 v9, 0
	v_mov_b32_e32 v10, 0
	v_mov_b32_e32 v11, 0
	v_mov_b32_e32 v4, 0
	v_mov_b32_e32 v5, 0
	v_mov_b32_e32 v6, 0
	v_mov_b32_e32 v7, 0
	v_mov_b32_e32 v0, 0
	v_mov_b32_e32 v1, 0
	v_mov_b32_e32 v2, 0
	v_mov_b32_e32 v3, 0
	v_mov_b32_e32 v28, 0
	v_mov_b32_e32 v29, 0
	v_mov_b32_e32 v30, 0
	v_mov_b32_e32 v31, 0
	v_mov_b32_e32 v24, 0
	v_mov_b32_e32 v25, 0
	v_mov_b32_e32 v26, 0
	v_mov_b32_e32 v27, 0
	v_mov_b32_e32 v20, 0
	v_mov_b32_e32 v21, 0
	v_mov_b32_e32 v22, 0
	v_mov_b32_e32 v23, 0
	v_mov_b32_e32 v16, 0
	v_mov_b32_e32 v17, 0
	v_mov_b32_e32 v18, 0
	v_mov_b32_e32 v19, 0
	s_waitcnt vmcnt(6)
	s_barrier
	ds_read_b128 v[44:47], v209 offset:0
	ds_read_b128 v[48:51], v209 offset:1024
	ds_read_b128 v[56:59], v209 offset:2048
	ds_read_b128 v[60:63], v209 offset:3072
	ds_read_b128 v[92:95], v210 offset:8192
	ds_read_b128 v[100:103], v210 offset:9216
	ds_read_b128 v[108:111], v210 offset:10240
	ds_read_b128 v[116:119], v210 offset:11264
	ds_read_b128 v[176:179], v210 offset:12288
	ds_read_b128 v[180:183], v210 offset:13312
	s_add_u32 m0, s11, 0xc000
	s_nop 0
	global_load_lds_dwordx4 v203, s[2:3]
	s_add_u32 m0, s11, 0xc400
	s_nop 0
	global_load_lds_dwordx4 v204, s[2:3]
	s_add_u32 m0, s12, 0xe000
	s_nop 0
	global_load_lds_dwordx4 v205, s[4:5]
	s_add_u32 m0, s12, 0xe400
	s_nop 0
	global_load_lds_dwordx4 v206, s[4:5]
	s_add_u32 m0, s12, 0xe800
	s_nop 0
	global_load_lds_dwordx4 v207, s[4:5]
	s_add_u32 m0, s12, 0xec00
	s_nop 0
	global_load_lds_dwordx4 v208, s[4:5]
	s_add_u32 s2, s2, 0x40
	s_addc_u32 s3, s3, 0
	s_add_u32 s4, s4, 0x40
	s_addc_u32 s5, s5, 0
	ds_read_b128 v[184:187], v210 offset:14336
	ds_read_b128 v[188:191], v210 offset:15360
	s_waitcnt lgkmcnt(7)
	v_mfma_f32_16x16x32_bf16 v[156:159], v[92:95], v[44:47], v[156:159]
	v_mfma_f32_16x16x32_bf16 v[124:127], v[92:95], v[48:51], v[124:127]
	v_mfma_f32_16x16x32_bf16 v[52:55], v[92:95], v[56:59], v[52:55]
	v_mfma_f32_16x16x32_bf16 v[12:15], v[92:95], v[60:63], v[12:15]
	s_waitcnt lgkmcnt(6)
	v_mfma_f32_16x16x32_bf16 v[152:155], v[100:103], v[44:47], v[152:155]
	v_mfma_f32_16x16x32_bf16 v[120:123], v[100:103], v[48:51], v[120:123]
	v_mfma_f32_16x16x32_bf16 v[40:43], v[100:103], v[56:59], v[40:43]
	v_mfma_f32_16x16x32_bf16 v[8:11], v[100:103], v[60:63], v[8:11]
	s_waitcnt lgkmcnt(5)
	v_mfma_f32_16x16x32_bf16 v[148:151], v[108:111], v[44:47], v[148:151]
	v_mfma_f32_16x16x32_bf16 v[112:115], v[108:111], v[48:51], v[112:115]
	v_mfma_f32_16x16x32_bf16 v[36:39], v[108:111], v[56:59], v[36:39]
	v_mfma_f32_16x16x32_bf16 v[4:7], v[108:111], v[60:63], v[4:7]
	s_waitcnt lgkmcnt(4)
	v_mfma_f32_16x16x32_bf16 v[144:147], v[116:119], v[44:47], v[144:147]
	v_mfma_f32_16x16x32_bf16 v[104:107], v[116:119], v[48:51], v[104:107]
	v_mfma_f32_16x16x32_bf16 v[32:35], v[116:119], v[56:59], v[32:35]
	v_mfma_f32_16x16x32_bf16 v[0:3], v[116:119], v[60:63], v[0:3]
	s_waitcnt lgkmcnt(3)
	v_mfma_f32_16x16x32_bf16 v[172:175], v[176:179], v[44:47], v[172:175]
	v_mfma_f32_16x16x32_bf16 v[140:143], v[176:179], v[48:51], v[140:143]
	v_mfma_f32_16x16x32_bf16 v[96:99], v[176:179], v[56:59], v[96:99]
	v_mfma_f32_16x16x32_bf16 v[28:31], v[176:179], v[60:63], v[28:31]
	s_waitcnt lgkmcnt(2)
	v_mfma_f32_16x16x32_bf16 v[168:171], v[180:183], v[44:47], v[168:171]
	v_mfma_f32_16x16x32_bf16 v[136:139], v[180:183], v[48:51], v[136:139]
	v_mfma_f32_16x16x32_bf16 v[88:91], v[180:183], v[56:59], v[88:91]
	v_mfma_f32_16x16x32_bf16 v[24:27], v[180:183], v[60:63], v[24:27]
	s_waitcnt lgkmcnt(0)
	s_mov_b32 s13, 5
.Lg2_loop:
	s_waitcnt vmcnt(6)
	s_barrier
	ds_read_b128 v[64:67], v209 offset:24576
	ds_read_b128 v[72:75], v209 offset:25600
	ds_read_b128 v[80:83], v209 offset:26624
	ds_read_b128 v[84:87], v209 offset:27648
	ds_read_b128 v[92:95], v210 offset:32768
	ds_read_b128 v[100:103], v210 offset:33792
	ds_read_b128 v[108:111], v210 offset:34816
	ds_read_b128 v[116:119], v210 offset:35840
	ds_read_b128 v[176:179], v210 offset:36864
	ds_read_b128 v[180:183], v210 offset:37888
	v_mfma_f32_16x16x32_bf16 v[164:167], v[184:187], v[44:47], v[164:167]
	s_add_u32 m0, s11, 0x0
	v_mfma_f32_16x16x32_bf16 v[132:135], v[184:187], v[48:51], v[132:135]
	global_load_lds_dwordx4 v203, s[2:3]
	s_add_u32 m0, s11, 0x400
	v_mfma_f32_16x16x32_bf16 v[76:79], v[184:187], v[56:59], v[76:79]
	global_load_lds_dwordx4 v204, s[2:3]
	s_add_u32 m0, s12, 0x2000
	v_mfma_f32_16x16x32_bf16 v[20:23], v[184:187], v[60:63], v[20:23]
	global_load_lds_dwordx4 v205, s[4:5]
	s_add_u32 m0, s12, 0x2400
	v_mfma_f32_16x16x32_bf16 v[160:163], v[188:191], v[44:47], v[160:163]
	global_load_lds_dwordx4 v206, s[4:5]
	s_add_u32 m0, s12, 0x2800
	v_mfma_f32_16x16x32_bf16 v[128:131], v[188:191], v[48:51], v[128:131]
	global_load_lds_dwordx4 v207, s[4:5]
	s_add_u32 m0, s12, 0x2c00
	v_mfma_f32_16x16x32_bf16 v[68:71], v[188:191], v[56:59], v[68:71]
	global_load_lds_dwordx4 v208, s[4:5]
	v_mfma_f32_16x16x32_bf16 v[16:19], v[188:191], v[60:63], v[16:19]
	s_add_u32 s2, s2, 0x40
	s_addc_u32 s3, s3, 0
	s_add_u32 s4, s4, 0x40
	s_addc_u32 s5, s5, 0
	ds_read_b128 v[184:187], v210 offset:38912
	ds_read_b128 v[188:191], v210 offset:39936
	s_waitcnt lgkmcnt(7)
	v_mfma_f32_16x16x32_bf16 v[156:159], v[92:95], v[64:67], v[156:159]
	v_mfma_f32_16x16x32_bf16 v[124:127], v[92:95], v[72:75], v[124:127]
	v_mfma_f32_16x16x32_bf16 v[52:55], v[92:95], v[80:83], v[52:55]
	v_mfma_f32_16x16x32_bf16 v[12:15], v[92:95], v[84:87], v[12:15]
	s_waitcnt lgkmcnt(6)
	v_mfma_f32_16x16x32_bf16 v[152:155], v[100:103], v[64:67], v[152:155]
	v_mfma_f32_16x16x32_bf16 v[120:123], v[100:103], v[72:75], v[120:123]
	v_mfma_f32_16x16x32_bf16 v[40:43], v[100:103], v[80:83], v[40:43]
	v_mfma_f32_16x16x32_bf16 v[8:11], v[100:103], v[84:87], v[8:11]
	s_waitcnt lgkmcnt(5)
	v_mfma_f32_16x16x32_bf16 v[148:151], v[108:111], v[64:67], v[148:151]
	v_mfma_f32_16x16x32_bf16 v[112:115], v[108:111], v[72:75], v[112:115]
	v_mfma_f32_16x16x32_bf16 v[36:39], v[108:111], v[80:83], v[36:39]
	v_mfma_f32_16x16x32_bf16 v[4:7], v[108:111], v[84:87], v[4:7]
	s_waitcnt lgkmcnt(4)
	v_mfma_f32_16x16x32_bf16 v[144:147], v[116:119], v[64:67], v[144:147]
	v_mfma_f32_16x16x32_bf16 v[104:107], v[116:119], v[72:75], v[104:107]
	v_mfma_f32_16x16x32_bf16 v[32:35], v[116:119], v[80:83], v[32:35]
	v_mfma_f32_16x16x32_bf16 v[0:3], v[116:119], v[84:87], v[0:3]
	s_waitcnt lgkmcnt(3)
	v_mfma_f32_16x16x32_bf16 v[172:175], v[176:179], v[64:67], v[172:175]
	v_mfma_f32_16x16x32_bf16 v[140:143], v[176:179], v[72:75], v[140:143]
	v_mfma_f32_16x16x32_bf16 v[96:99], v[176:179], v[80:83], v[96:99]
	v_mfma_f32_16x16x32_bf16 v[28:31], v[176:179], v[84:87], v[28:31]
	s_waitcnt lgkmcnt(2)
	v_mfma_f32_16x16x32_bf16 v[168:171], v[180:183], v[64:67], v[168:171]
	v_mfma_f32_16x16x32_bf16 v[136:139], v[180:183], v[72:75], v[136:139]
	v_mfma_f32_16x16x32_bf16 v[88:91], v[180:183], v[80:83], v[88:91]
	v_mfma_f32_16x16x32_bf16 v[24:27], v[180:183], v[84:87], v[24:27]
	s_waitcnt lgkmcnt(0)
	s_waitcnt vmcnt(6)
	s_barrier
	ds_read_b128 v[44:47], v209 offset:49152
	ds_read_b128 v[48:51], v209 offset:50176
	ds_read_b128 v[56:59], v209 offset:51200
	ds_read_b128 v[60:63], v209 offset:52224
	ds_read_b128 v[92:95], v210 offset:57344
	ds_read_b128 v[100:103], v210 offset:58368
	ds_read_b128 v[108:111], v210 offset:59392
	ds_read_b128 v[116:119], v210 offset:60416
	ds_read_b128 v[176:179], v210 offset:61440
	ds_read_b128 v[180:183], v210 offset:62464
	v_mfma_f32_16x16x32_bf16 v[164:167], v[184:187], v[64:67], v[164:167]
	s_add_u32 m0, s11, 0x6000
	v_mfma_f32_16x16x32_bf16 v[132:135], v[184:187], v[72:75], v[132:135]
	global_load_lds_dwordx4 v203, s[2:3]
	s_add_u32 m0, s11, 0x6400
	v_mfma_f32_16x16x32_bf16 v[76:79], v[184:187], v[80:83], v[76:79]
	global_load_lds_dwordx4 v204, s[2:3]
	s_add_u32 m0, s12, 0x8000
	v_mfma_f32_16x16x32_bf16 v[20:23], v[184:187], v[84:87], v[20:23]
	global_load_lds_dwordx4 v205, s[4:5]
	s_add_u32 m0, s12, 0x8400
	v_mfma_f32_16x16x32_bf16 v[160:163], v[188:191], v[64:67], v[160:163]
	global_load_lds_dwordx4 v206, s[4:5]
	s_add_u32 m0, s12, 0x8800
	v_mfma_f32_16x16x32_bf16 v[128:131], v[188:191], v[72:75], v[128:131]
	global_load_lds_dwordx4 v207, s[4:5]
	s_add_u32 m0, s12, 0x8c00
	v_mfma_f32_16x16x32_bf16 v[68:71], v[188:191], v[80:83], v[68:71]
	global_load_lds_dwordx4 v208, s[4:5]
	v_mfma_f32_16x16x32_bf16 v[16:19], v[188:191], v[84:87], v[16:19]
	s_add_u32 s2, s2, 0x40
	s_addc_u32 s3, s3, 0
	s_add_u32 s4, s4, 0x40
	s_addc_u32 s5, s5, 0
	ds_read_b128 v[184:187], v210 offset:63488
	ds_read_b128 v[188:191], v210 offset:64512
	s_waitcnt lgkmcnt(7)
	v_mfma_f32_16x16x32_bf16 v[156:159], v[92:95], v[44:47], v[156:159]
	v_mfma_f32_16x16x32_bf16 v[124:127], v[92:95], v[48:51], v[124:127]
	v_mfma_f32_16x16x32_bf16 v[52:55], v[92:95], v[56:59], v[52:55]
	v_mfma_f32_16x16x32_bf16 v[12:15], v[92:95], v[60:63], v[12:15]
	s_waitcnt lgkmcnt(6)
	v_mfma_f32_16x16x32_bf16 v[152:155], v[100:103], v[44:47], v[152:155]
	v_mfma_f32_16x16x32_bf16 v[120:123], v[100:103], v[48:51], v[120:123]
	v_mfma_f32_16x16x32_bf16 v[40:43], v[100:103], v[56:59], v[40:43]
	v_mfma_f32_16x16x32_bf16 v[8:11], v[100:103], v[60:63], v[8:11]
	s_waitcnt lgkmcnt(5)
	v_mfma_f32_16x16x32_bf16 v[148:151], v[108:111], v[44:47], v[148:151]
	v_mfma_f32_16x16x32_bf16 v[112:115], v[108:111], v[48:51], v[112:115]
	v_mfma_f32_16x16x32_bf16 v[36:39], v[108:111], v[56:59], v[36:39]
	v_mfma_f32_16x16x32_bf16 v[4:7], v[108:111], v[60:63], v[4:7]
	s_waitcnt lgkmcnt(4)
	v_mfma_f32_16x16x32_bf16 v[144:147], v[116:119], v[44:47], v[144:147]
	v_mfma_f32_16x16x32_bf16 v[104:107], v[116:119], v[48:51], v[104:107]
	v_mfma_f32_16x16x32_bf16 v[32:35], v[116:119], v[56:59], v[32:35]
	v_mfma_f32_16x16x32_bf16 v[0:3], v[116:119], v[60:63], v[0:3]
	s_waitcnt lgkmcnt(3)
	v_mfma_f32_16x16x32_bf16 v[172:175], v[176:179], v[44:47], v[172:175]
	v_mfma_f32_16x16x32_bf16 v[140:143], v[176:179], v[48:51], v[140:143]
	v_mfma_f32_16x16x32_bf16 v[96:99], v[176:179], v[56:59], v[96:99]
	v_mfma_f32_16x16x32_bf16 v[28:31], v[176:179], v[60:63], v[28:31]
	s_waitcnt lgkmcnt(2)
	v_mfma_f32_16x16x32_bf16 v[168:171], v[180:183], v[44:47], v[168:171]
	v_mfma_f32_16x16x32_bf16 v[136:139], v[180:183], v[48:51], v[136:139]
	v_mfma_f32_16x16x32_bf16 v[88:91], v[180:183], v[56:59], v[88:91]
	v_mfma_f32_16x16x32_bf16 v[24:27], v[180:183], v[60:63], v[24:27]
	s_waitcnt lgkmcnt(0)
	s_waitcnt vmcnt(6)
	s_barrier
	ds_read_b128 v[64:67], v209 offset:0
	ds_read_b128 v[72:75], v209 offset:1024
	ds_read_b128 v[80:83], v209 offset:2048
	ds_read_b128 v[84:87], v209 offset:3072
	ds_read_b128 v[92:95], v210 offset:8192
	ds_read_b128 v[100:103], v210 offset:9216
	ds_read_b128 v[108:111], v210 offset:10240
	ds_read_b128 v[116:119], v210 offset:11264
	ds_read_b128 v[176:179], v210 offset:12288
	ds_read_b128 v[180:183], v210 offset:13312
	v_mfma_f32_16x16x32_bf16 v[164:167], v[184:187], v[44:47], v[164:167]
	s_add_u32 m0, s11, 0xc000
	v_mfma_f32_16x16x32_bf16 v[132:135], v[184:187], v[48:51], v[132:135]
	global_load_lds_dwordx4 v203, s[2:3]
	s_add_u32 m0, s11, 0xc400
	v_mfma_f32_16x16x32_bf16 v[76:79], v[184:187], v[56:59], v[76:79]
	global_load_lds_dwordx4 v204, s[2:3]
	s_add_u32 m0, s12, 0xe000
	v_mfma_f32_16x16x32_bf16 v[20:23], v[184:187], v[60:63], v[20:23]
	global_load_lds_dwordx4 v205, s[4:5]
	s_add_u32 m0, s12, 0xe400
	v_mfma_f32_16x16x32_bf16 v[160:163], v[188:191], v[44:47], v[160:163]
	global_load_lds_dwordx4 v206, s[4:5]
	s_add_u32 m0, s12, 0xe800
	v_mfma_f32_16x16x32_bf16 v[128:131], v[188:191], v[48:51], v[128:131]
	global_load_lds_dwordx4 v207, s[4:5]
	s_add_u32 m0, s12, 0xec00
	v_mfma_f32_16x16x32_bf16 v[68:71], v[188:191], v[56:59], v[68:71]
	global_load_lds_dwordx4 v208, s[4:5]
	v_mfma_f32_16x16x32_bf16 v[16:19], v[188:191], v[60:63], v[16:19]
	s_add_u32 s2, s2, 0x40
	s_addc_u32 s3, s3, 0
	s_add_u32 s4, s4, 0x40
	s_addc_u32 s5, s5, 0
	ds_read_b128 v[184:187], v210 offset:14336
	ds_read_b128 v[188:191], v210 offset:15360
	s_waitcnt lgkmcnt(7)
	v_mfma_f32_16x16x32_bf16 v[156:159], v[92:95], v[64:67], v[156:159]
	v_mfma_f32_16x16x32_bf16 v[124:127], v[92:95], v[72:75], v[124:127]
	v_mfma_f32_16x16x32_bf16 v[52:55], v[92:95], v[80:83], v[52:55]
	v_mfma_f32_16x16x32_bf16 v[12:15], v[92:95], v[84:87], v[12:15]
	s_waitcnt lgkmcnt(6)
	v_mfma_f32_16x16x32_bf16 v[152:155], v[100:103], v[64:67], v[152:155]
	v_mfma_f32_16x16x32_bf16 v[120:123], v[100:103], v[72:75], v[120:123]
	v_mfma_f32_16x16x32_bf16 v[40:43], v[100:103], v[80:83], v[40:43]
	v_mfma_f32_16x16x32_bf16 v[8:11], v[100:103], v[84:87], v[8:11]
	s_waitcnt lgkmcnt(5)
	v_mfma_f32_16x16x32_bf16 v[148:151], v[108:111], v[64:67], v[148:151]
	v_mfma_f32_16x16x32_bf16 v[112:115], v[108:111], v[72:75], v[112:115]
	v_mfma_f32_16x16x32_bf16 v[36:39], v[108:111], v[80:83], v[36:39]
	v_mfma_f32_16x16x32_bf16 v[4:7], v[108:111], v[84:87], v[4:7]
	s_waitcnt lgkmcnt(4)
	v_mfma_f32_16x16x32_bf16 v[144:147], v[116:119], v[64:67], v[144:147]
	v_mfma_f32_16x16x32_bf16 v[104:107], v[116:119], v[72:75], v[104:107]
	v_mfma_f32_16x16x32_bf16 v[32:35], v[116:119], v[80:83], v[32:35]
	v_mfma_f32_16x16x32_bf16 v[0:3], v[116:119], v[84:87], v[0:3]
	s_waitcnt lgkmcnt(3)
	v_mfma_f32_16x16x32_bf16 v[172:175], v[176:179], v[64:67], v[172:175]
	v_mfma_f32_16x16x32_bf16 v[140:143], v[176:179], v[72:75], v[140:143]
	v_mfma_f32_16x16x32_bf16 v[96:99], v[176:179], v[80:83], v[96:99]
	v_mfma_f32_16x16x32_bf16 v[28:31], v[176:179], v[84:87], v[28:31]
	s_waitcnt lgkmcnt(2)
	v_mfma_f32_16x16x32_bf16 v[168:171], v[180:183], v[64:67], v[168:171]
	v_mfma_f32_16x16x32_bf16 v[136:139], v[180:183], v[72:75], v[136:139]
	v_mfma_f32_16x16x32_bf16 v[88:91], v[180:183], v[80:83], v[88:91]
	v_mfma_f32_16x16x32_bf16 v[24:27], v[180:183], v[84:87], v[24:27]
	s_waitcnt lgkmcnt(0)
	s_waitcnt vmcnt(6)
	s_barrier
	ds_read_b128 v[44:47], v209 offset:24576
	ds_read_b128 v[48:51], v209 offset:25600
	ds_read_b128 v[56:59], v209 offset:26624
	ds_read_b128 v[60:63], v209 offset:27648
	ds_read_b128 v[92:95], v210 offset:32768
	ds_read_b128 v[100:103], v210 offset:33792
	ds_read_b128 v[108:111], v210 offset:34816
	ds_read_b128 v[116:119], v210 offset:35840
	ds_read_b128 v[176:179], v210 offset:36864
	ds_read_b128 v[180:183], v210 offset:37888
	v_mfma_f32_16x16x32_bf16 v[164:167], v[184:187], v[64:67], v[164:167]
	s_add_u32 m0, s11, 0x0
	v_mfma_f32_16x16x32_bf16 v[132:135], v[184:187], v[72:75], v[132:135]
	global_load_lds_dwordx4 v203, s[2:3]
	s_add_u32 m0, s11, 0x400
	v_mfma_f32_16x16x32_bf16 v[76:79], v[184:187], v[80:83], v[76:79]
	global_load_lds_dwordx4 v204, s[2:3]
	s_add_u32 m0, s12, 0x2000
	v_mfma_f32_16x16x32_bf16 v[20:23], v[184:187], v[84:87], v[20:23]
	global_load_lds_dwordx4 v205, s[4:5]
	s_add_u32 m0, s12, 0x2400
	v_mfma_f32_16x16x32_bf16 v[160:163], v[188:191], v[64:67], v[160:163]
	global_load_lds_dwordx4 v206, s[4:5]
	s_add_u32 m0, s12, 0x2800
	v_mfma_f32_16x16x32_bf16 v[128:131], v[188:191], v[72:75], v[128:131]
	global_load_lds_dwordx4 v207, s[4:5]
	s_add_u32 m0, s12, 0x2c00
	v_mfma_f32_16x16x32_bf16 v[68:71], v[188:191], v[80:83], v[68:71]
	global_load_lds_dwordx4 v208, s[4:5]
	v_mfma_f32_16x16x32_bf16 v[16:19], v[188:191], v[84:87], v[16:19]
	s_add_u32 s2, s2, 0x40
	s_addc_u32 s3, s3, 0
	s_add_u32 s4, s4, 0x40
	s_addc_u32 s5, s5, 0
	ds_read_b128 v[184:187], v210 offset:38912
	ds_read_b128 v[188:191], v210 offset:39936
	s_waitcnt lgkmcnt(7)
	v_mfma_f32_16x16x32_bf16 v[156:159], v[92:95], v[44:47], v[156:159]
	v_mfma_f32_16x16x32_bf16 v[124:127], v[92:95], v[48:51], v[124:127]
	v_mfma_f32_16x16x32_bf16 v[52:55], v[92:95], v[56:59], v[52:55]
	v_mfma_f32_16x16x32_bf16 v[12:15], v[92:95], v[60:63], v[12:15]
	s_waitcnt lgkmcnt(6)
	v_mfma_f32_16x16x32_bf16 v[152:155], v[100:103], v[44:47], v[152:155]
	v_mfma_f32_16x16x32_bf16 v[120:123], v[100:103], v[48:51], v[120:123]
	v_mfma_f32_16x16x32_bf16 v[40:43], v[100:103], v[56:59], v[40:43]
	v_mfma_f32_16x16x32_bf16 v[8:11], v[100:103], v[60:63], v[8:11]
	s_waitcnt lgkmcnt(5)
	v_mfma_f32_16x16x32_bf16 v[148:151], v[108:111], v[44:47], v[148:151]
	v_mfma_f32_16x16x32_bf16 v[112:115], v[108:111], v[48:51], v[112:115]
	v_mfma_f32_16x16x32_bf16 v[36:39], v[108:111], v[56:59], v[36:39]
	v_mfma_f32_16x16x32_bf16 v[4:7], v[108:111], v[60:63], v[4:7]
	s_waitcnt lgkmcnt(4)
	v_mfma_f32_16x16x32_bf16 v[144:147], v[116:119], v[44:47], v[144:147]
	v_mfma_f32_16x16x32_bf16 v[104:107], v[116:119], v[48:51], v[104:107]
	v_mfma_f32_16x16x32_bf16 v[32:35], v[116:119], v[56:59], v[32:35]
	v_mfma_f32_16x16x32_bf16 v[0:3], v[116:119], v[60:63], v[0:3]
	s_waitcnt lgkmcnt(3)
	v_mfma_f32_16x16x32_bf16 v[172:175], v[176:179], v[44:47], v[172:175]
	v_mfma_f32_16x16x32_bf16 v[140:143], v[176:179], v[48:51], v[140:143]
	v_mfma_f32_16x16x32_bf16 v[96:99], v[176:179], v[56:59], v[96:99]
	v_mfma_f32_16x16x32_bf16 v[28:31], v[176:179], v[60:63], v[28:31]
	s_waitcnt lgkmcnt(2)
	v_mfma_f32_16x16x32_bf16 v[168:171], v[180:183], v[44:47], v[168:171]
	v_mfma_f32_16x16x32_bf16 v[136:139], v[180:183], v[48:51], v[136:139]
	v_mfma_f32_16x16x32_bf16 v[88:91], v[180:183], v[56:59], v[88:91]
	v_mfma_f32_16x16x32_bf16 v[24:27], v[180:183], v[60:63], v[24:27]
	s_waitcnt lgkmcnt(0)
	s_waitcnt vmcnt(6)
	s_barrier
	ds_read_b128 v[64:67], v209 offset:49152
	ds_read_b128 v[72:75], v209 offset:50176
	ds_read_b128 v[80:83], v209 offset:51200
	ds_read_b128 v[84:87], v209 offset:52224
	ds_read_b128 v[92:95], v210 offset:57344
	ds_read_b128 v[100:103], v210 offset:58368
	ds_read_b128 v[108:111], v210 offset:59392
	ds_read_b128 v[116:119], v210 offset:60416
	ds_read_b128 v[176:179], v210 offset:61440
	ds_read_b128 v[180:183], v210 offset:62464
	v_mfma_f32_16x16x32_bf16 v[164:167], v[184:187], v[44:47], v[164:167]
	s_add_u32 m0, s11, 0x6000
	v_mfma_f32_16x16x32_bf16 v[132:135], v[184:187], v[48:51], v[132:135]
	global_load_lds_dwordx4 v203, s[2:3]
	s_add_u32 m0, s11, 0x6400
	v_mfma_f32_16x16x32_bf16 v[76:79], v[184:187], v[56:59], v[76:79]
	global_load_lds_dwordx4 v204, s[2:3]
	s_add_u32 m0, s12, 0x8000
	v_mfma_f32_16x16x32_bf16 v[20:23], v[184:187], v[60:63], v[20:23]
	global_load_lds_dwordx4 v205, s[4:5]
	s_add_u32 m0, s12, 0x8400
	v_mfma_f32_16x16x32_bf16 v[160:163], v[188:191], v[44:47], v[160:163]
	global_load_lds_dwordx4 v206, s[4:5]
	s_add_u32 m0, s12, 0x8800
	v_mfma_f32_16x16x32_bf16 v[128:131], v[188:191], v[48:51], v[128:131]
	global_load_lds_dwordx4 v207, s[4:5]
	s_add_u32 m0, s12, 0x8c00
	v_mfma_f32_16x16x32_bf16 v[68:71], v[188:191], v[56:59], v[68:71]
	global_load_lds_dwordx4 v208, s[4:5]
	v_mfma_f32_16x16x32_bf16 v[16:19], v[188:191], v[60:63], v[16:19]
	s_add_u32 s2, s2, 0x40
	s_addc_u32 s3, s3, 0
	s_add_u32 s4, s4, 0x40
	s_addc_u32 s5, s5, 0
	ds_read_b128 v[184:187], v210 offset:63488
	ds_read_b128 v[188:191], v210 offset:64512
	s_waitcnt lgkmcnt(7)
	v_mfma_f32_16x16x32_bf16 v[156:159], v[92:95], v[64:67], v[156:159]
	v_mfma_f32_16x16x32_bf16 v[124:127], v[92:95], v[72:75], v[124:127]
	v_mfma_f32_16x16x32_bf16 v[52:55], v[92:95], v[80:83], v[52:55]
	v_mfma_f32_16x16x32_bf16 v[12:15], v[92:95], v[84:87], v[12:15]
	s_waitcnt lgkmcnt(6)
	v_mfma_f32_16x16x32_bf16 v[152:155], v[100:103], v[64:67], v[152:155]
	v_mfma_f32_16x16x32_bf16 v[120:123], v[100:103], v[72:75], v[120:123]
	v_mfma_f32_16x16x32_bf16 v[40:43], v[100:103], v[80:83], v[40:43]
	v_mfma_f32_16x16x32_bf16 v[8:11], v[100:103], v[84:87], v[8:11]
	s_waitcnt lgkmcnt(5)
	v_mfma_f32_16x16x32_bf16 v[148:151], v[108:111], v[64:67], v[148:151]
	v_mfma_f32_16x16x32_bf16 v[112:115], v[108:111], v[72:75], v[112:115]
	v_mfma_f32_16x16x32_bf16 v[36:39], v[108:111], v[80:83], v[36:39]
	v_mfma_f32_16x16x32_bf16 v[4:7], v[108:111], v[84:87], v[4:7]
	s_waitcnt lgkmcnt(4)
	v_mfma_f32_16x16x32_bf16 v[144:147], v[116:119], v[64:67], v[144:147]
	v_mfma_f32_16x16x32_bf16 v[104:107], v[116:119], v[72:75], v[104:107]
	v_mfma_f32_16x16x32_bf16 v[32:35], v[116:119], v[80:83], v[32:35]
	v_mfma_f32_16x16x32_bf16 v[0:3], v[116:119], v[84:87], v[0:3]
	s_waitcnt lgkmcnt(3)
	v_mfma_f32_16x16x32_bf16 v[172:175], v[176:179], v[64:67], v[172:175]
	v_mfma_f32_16x16x32_bf16 v[140:143], v[176:179], v[72:75], v[140:143]
	v_mfma_f32_16x16x32_bf16 v[96:99], v[176:179], v[80:83], v[96:99]
	v_mfma_f32_16x16x32_bf16 v[28:31], v[176:179], v[84:87], v[28:31]
	s_waitcnt lgkmcnt(2)
	v_mfma_f32_16x16x32_bf16 v[168:171], v[180:183], v[64:67], v[168:171]
	v_mfma_f32_16x16x32_bf16 v[136:139], v[180:183], v[72:75], v[136:139]
	v_mfma_f32_16x16x32_bf16 v[88:91], v[180:183], v[80:83], v[88:91]
	v_mfma_f32_16x16x32_bf16 v[24:27], v[180:183], v[84:87], v[24:27]
	s_waitcnt lgkmcnt(0)
	s_waitcnt vmcnt(6)
	s_barrier
	ds_read_b128 v[44:47], v209 offset:0
	ds_read_b128 v[48:51], v209 offset:1024
	ds_read_b128 v[56:59], v209 offset:2048
	ds_read_b128 v[60:63], v209 offset:3072
	ds_read_b128 v[92:95], v210 offset:8192
	ds_read_b128 v[100:103], v210 offset:9216
	ds_read_b128 v[108:111], v210 offset:10240
	ds_read_b128 v[116:119], v210 offset:11264
	ds_read_b128 v[176:179], v210 offset:12288
	ds_read_b128 v[180:183], v210 offset:13312
	v_mfma_f32_16x16x32_bf16 v[164:167], v[184:187], v[64:67], v[164:167]
	s_add_u32 m0, s11, 0xc000
	v_mfma_f32_16x16x32_bf16 v[132:135], v[184:187], v[72:75], v[132:135]
	global_load_lds_dwordx4 v203, s[2:3]
	s_add_u32 m0, s11, 0xc400
	v_mfma_f32_16x16x32_bf16 v[76:79], v[184:187], v[80:83], v[76:79]
	global_load_lds_dwordx4 v204, s[2:3]
	s_add_u32 m0, s12, 0xe000
	v_mfma_f32_16x16x32_bf16 v[20:23], v[184:187], v[84:87], v[20:23]
	global_load_lds_dwordx4 v205, s[4:5]
	s_add_u32 m0, s12, 0xe400
	v_mfma_f32_16x16x32_bf16 v[160:163], v[188:191], v[64:67], v[160:163]
	global_load_lds_dwordx4 v206, s[4:5]
	s_add_u32 m0, s12, 0xe800
	v_mfma_f32_16x16x32_bf16 v[128:131], v[188:191], v[72:75], v[128:131]
	global_load_lds_dwordx4 v207, s[4:5]
	s_add_u32 m0, s12, 0xec00
	v_mfma_f32_16x16x32_bf16 v[68:71], v[188:191], v[80:83], v[68:71]
	global_load_lds_dwordx4 v208, s[4:5]
	v_mfma_f32_16x16x32_bf16 v[16:19], v[188:191], v[84:87], v[16:19]
	s_add_u32 s2, s2, 0x40
	s_addc_u32 s3, s3, 0
	s_add_u32 s4, s4, 0x40
	s_addc_u32 s5, s5, 0
	ds_read_b128 v[184:187], v210 offset:14336
	ds_read_b128 v[188:191], v210 offset:15360
	s_waitcnt lgkmcnt(7)
	v_mfma_f32_16x16x32_bf16 v[156:159], v[92:95], v[44:47], v[156:159]
	v_mfma_f32_16x16x32_bf16 v[124:127], v[92:95], v[48:51], v[124:127]
	v_mfma_f32_16x16x32_bf16 v[52:55], v[92:95], v[56:59], v[52:55]
	v_mfma_f32_16x16x32_bf16 v[12:15], v[92:95], v[60:63], v[12:15]
	s_waitcnt lgkmcnt(6)
	v_mfma_f32_16x16x32_bf16 v[152:155], v[100:103], v[44:47], v[152:155]
	v_mfma_f32_16x16x32_bf16 v[120:123], v[100:103], v[48:51], v[120:123]
	v_mfma_f32_16x16x32_bf16 v[40:43], v[100:103], v[56:59], v[40:43]
	v_mfma_f32_16x16x32_bf16 v[8:11], v[100:103], v[60:63], v[8:11]
	s_waitcnt lgkmcnt(5)
	v_mfma_f32_16x16x32_bf16 v[148:151], v[108:111], v[44:47], v[148:151]
	v_mfma_f32_16x16x32_bf16 v[112:115], v[108:111], v[48:51], v[112:115]
	v_mfma_f32_16x16x32_bf16 v[36:39], v[108:111], v[56:59], v[36:39]
	v_mfma_f32_16x16x32_bf16 v[4:7], v[108:111], v[60:63], v[4:7]
	s_waitcnt lgkmcnt(4)
	v_mfma_f32_16x16x32_bf16 v[144:147], v[116:119], v[44:47], v[144:147]
	v_mfma_f32_16x16x32_bf16 v[104:107], v[116:119], v[48:51], v[104:107]
	v_mfma_f32_16x16x32_bf16 v[32:35], v[116:119], v[56:59], v[32:35]
	v_mfma_f32_16x16x32_bf16 v[0:3], v[116:119], v[60:63], v[0:3]
	s_waitcnt lgkmcnt(3)
	v_mfma_f32_16x16x32_bf16 v[172:175], v[176:179], v[44:47], v[172:175]
	v_mfma_f32_16x16x32_bf16 v[140:143], v[176:179], v[48:51], v[140:143]
	v_mfma_f32_16x16x32_bf16 v[96:99], v[176:179], v[56:59], v[96:99]
	v_mfma_f32_16x16x32_bf16 v[28:31], v[176:179], v[60:63], v[28:31]
	s_waitcnt lgkmcnt(2)
	v_mfma_f32_16x16x32_bf16 v[168:171], v[180:183], v[44:47], v[168:171]
	v_mfma_f32_16x16x32_bf16 v[136:139], v[180:183], v[48:51], v[136:139]
	v_mfma_f32_16x16x32_bf16 v[88:91], v[180:183], v[56:59], v[88:91]
	v_mfma_f32_16x16x32_bf16 v[24:27], v[180:183], v[60:63], v[24:27]
	s_waitcnt lgkmcnt(0)
	s_sub_u32 s13, s13, 1
	s_cmp_lg_u32 s13, 0
	s_cbranch_scc1 .Lg2_loop
	s_waitcnt vmcnt(6)
	s_barrier
	ds_read_b128 v[64:67], v209 offset:24576
	ds_read_b128 v[72:75], v209 offset:25600
	ds_read_b128 v[80:83], v209 offset:26624
	ds_read_b128 v[84:87], v209 offset:27648
	ds_read_b128 v[92:95], v210 offset:32768
	ds_read_b128 v[100:103], v210 offset:33792
	ds_read_b128 v[108:111], v210 offset:34816
	ds_read_b128 v[116:119], v210 offset:35840
	ds_read_b128 v[176:179], v210 offset:36864
	ds_read_b128 v[180:183], v210 offset:37888
	v_mfma_f32_16x16x32_bf16 v[164:167], v[184:187], v[44:47], v[164:167]
	v_mfma_f32_16x16x32_bf16 v[132:135], v[184:187], v[48:51], v[132:135]
	v_mfma_f32_16x16x32_bf16 v[76:79], v[184:187], v[56:59], v[76:79]
	v_mfma_f32_16x16x32_bf16 v[20:23], v[184:187], v[60:63], v[20:23]
	v_mfma_f32_16x16x32_bf16 v[160:163], v[188:191], v[44:47], v[160:163]
	v_mfma_f32_16x16x32_bf16 v[128:131], v[188:191], v[48:51], v[128:131]
	v_mfma_f32_16x16x32_bf16 v[68:71], v[188:191], v[56:59], v[68:71]
	v_mfma_f32_16x16x32_bf16 v[16:19], v[188:191], v[60:63], v[16:19]
	ds_read_b128 v[184:187], v210 offset:38912
	ds_read_b128 v[188:191], v210 offset:39936
	s_waitcnt lgkmcnt(7)
	v_mfma_f32_16x16x32_bf16 v[156:159], v[92:95], v[64:67], v[156:159]
	v_mfma_f32_16x16x32_bf16 v[124:127], v[92:95], v[72:75], v[124:127]
	v_mfma_f32_16x16x32_bf16 v[52:55], v[92:95], v[80:83], v[52:55]
	v_mfma_f32_16x16x32_bf16 v[12:15], v[92:95], v[84:87], v[12:15]
	s_waitcnt lgkmcnt(6)
	v_mfma_f32_16x16x32_bf16 v[152:155], v[100:103], v[64:67], v[152:155]
	v_mfma_f32_16x16x32_bf16 v[120:123], v[100:103], v[72:75], v[120:123]
	v_mfma_f32_16x16x32_bf16 v[40:43], v[100:103], v[80:83], v[40:43]
	v_mfma_f32_16x16x32_bf16 v[8:11], v[100:103], v[84:87], v[8:11]
	s_waitcnt lgkmcnt(5)
	v_mfma_f32_16x16x32_bf16 v[148:151], v[108:111], v[64:67], v[148:151]
	v_mfma_f32_16x16x32_bf16 v[112:115], v[108:111], v[72:75], v[112:115]
	v_mfma_f32_16x16x32_bf16 v[36:39], v[108:111], v[80:83], v[36:39]
	v_mfma_f32_16x16x32_bf16 v[4:7], v[108:111], v[84:87], v[4:7]
	s_waitcnt lgkmcnt(4)
	v_mfma_f32_16x16x32_bf16 v[144:147], v[116:119], v[64:67], v[144:147]
	v_mfma_f32_16x16x32_bf16 v[104:107], v[116:119], v[72:75], v[104:107]
	v_mfma_f32_16x16x32_bf16 v[32:35], v[116:119], v[80:83], v[32:35]
	v_mfma_f32_16x16x32_bf16 v[0:3], v[116:119], v[84:87], v[0:3]
	s_waitcnt lgkmcnt(3)
	v_mfma_f32_16x16x32_bf16 v[172:175], v[176:179], v[64:67], v[172:175]
	v_mfma_f32_16x16x32_bf16 v[140:143], v[176:179], v[72:75], v[140:143]
	v_mfma_f32_16x16x32_bf16 v[96:99], v[176:179], v[80:83], v[96:99]
	v_mfma_f32_16x16x32_bf16 v[28:31], v[176:179], v[84:87], v[28:31]
	s_waitcnt lgkmcnt(2)
	v_mfma_f32_16x16x32_bf16 v[168:171], v[180:183], v[64:67], v[168:171]
	v_mfma_f32_16x16x32_bf16 v[136:139], v[180:183], v[72:75], v[136:139]
	v_mfma_f32_16x16x32_bf16 v[88:91], v[180:183], v[80:83], v[88:91]
	v_mfma_f32_16x16x32_bf16 v[24:27], v[180:183], v[84:87], v[24:27]
	s_waitcnt lgkmcnt(0)
	v_mfma_f32_16x16x32_bf16 v[164:167], v[184:187], v[64:67], v[164:167]
	v_mfma_f32_16x16x32_bf16 v[132:135], v[184:187], v[72:75], v[132:135]
	v_mfma_f32_16x16x32_bf16 v[76:79], v[184:187], v[80:83], v[76:79]
	v_mfma_f32_16x16x32_bf16 v[20:23], v[184:187], v[84:87], v[20:23]
	v_mfma_f32_16x16x32_bf16 v[160:163], v[188:191], v[64:67], v[160:163]
	v_mfma_f32_16x16x32_bf16 v[128:131], v[188:191], v[72:75], v[128:131]
	v_mfma_f32_16x16x32_bf16 v[68:71], v[188:191], v[80:83], v[68:71]
	v_mfma_f32_16x16x32_bf16 v[16:19], v[188:191], v[84:87], v[16:19]
	s_waitcnt vmcnt(0)
	s_nop 7
	s_nop 7
	s_branch .LBB0_502

.LBB0_529:
	s_setprio 0
	s_barrier
	s_mov_b64 s[2:3], exec
	v_readlane_b32 s4, v253, 30
	v_readlane_b32 s5, v253, 31
	s_and_b64 s[4:5], s[2:3], s[4:5]
	s_mov_b64 exec, s[4:5]
	s_cbranch_execz .LBB0_533
	s_mov_b64 s[8:9], exec
	s_waitcnt vmcnt(0)
	v_mbcnt_lo_u32_b32 v0, s8, 0
	v_mbcnt_hi_u32_b32 v0, s9, v0
	v_cmp_eq_u32_e32 vcc, 0, v0
	s_and_saveexec_b64 s[4:5], vcc
	s_cbranch_execz .LBB0_532
	s_bcnt1_i32_b64 s8, s[8:9]
	v_mov_b32_e32 v1, s8
	v_readlane_b32 s8, v255, 28
	v_readlane_b32 s9, v255, 29
	s_nop 4
	global_atomic_add v1, v201, v1, s[8:9] offset:4 sc0

.LBB0_758:
	s_andn2_b64 vcc, exec, s[2:3]
	s_cbranch_vccnz .LBB0_527
	s_setprio 3
	s_waitcnt vmcnt(11)
	v_mov_b32_e32 v40, v216
	s_movk_i32 s2, 0x1000
	s_nop 0
	v_cmp_gt_i32_e64 s[8:9], s2, v40
	s_movk_i32 s2, 0xfff
	v_cmp_lt_i32_e32 vcc, s2, v40
	s_waitcnt vmcnt(8)
	v_lshlrev_b32_e32 v43, 2, v40
	s_and_saveexec_b64 s[2:3], vcc
	s_xor_b64 s[2:3], exec, s[2:3]
	v_lshlrev_b32_e32 v43, 2, v40
	s_andn2_saveexec_b64 s[2:3], s[2:3]
	s_cbranch_execz .LBB0_765
	v_add_u32_e32 v0, 0xffffff00, v40
	s_mov_b64 s[4:5], 0
	v_mov_b32_e32 v1, v43
	s_movk_i32 s10, 0xeff

.LBB0_896:
	s_andn2_b64 vcc, exec, s[2:3]
	s_cbranch_vccnz .LBB0_890
	v_readlane_b32 s11, v254, 62
	v_readlane_b32 s12, v254, 60
	v_readlane_b32 s2, v253, 4
	v_readlane_b32 s3, v253, 5
	s_lshl_b32 s13, s11, 18
	s_add_u32 s2, s2, s13
	s_addc_u32 s3, s3, 0
	s_lshl_b32 s13, s12, 19
	s_add_u32 s4, s50, 0x65d0000
	s_addc_u32 s5, s51, 0
	s_add_u32 s4, s4, s13
	s_addc_u32 s5, s5, 0
	v_and_b32_e32 v152, 63, v216
	v_lshrrev_b32_e32 v153, 6, v216
	v_lshrrev_b32_e32 v154, 2, v152
	v_and_b32_e32 v155, 3, v152
	v_readfirstlane_b32 s11, v153
	v_lshrrev_b32_e32 v156, 3, v154
	v_mul_u32_u24_e32 v156, 3, v156
	v_xor_b32_e32 v156, v155, v156
	v_lshlrev_b32_e32 v156, 4, v156
	v_lshl_add_u32 v157, v153, 5, v154
	v_lshl_add_u32 v203, v157, 11, v156
	v_add_u32_e32 v204, 0x8000, v203
	v_lshl_add_u32 v157, v153, 6, v154
	v_lshl_add_u32 v205, v157, 11, v156
	v_add_u32_e32 v206, 0x8000, v205
	v_add_u32_e32 v207, 0x10000, v205
	v_add_u32_e32 v208, 0x18000, v205
	v_and_b32_e32 v158, 15, v152
	v_lshrrev_b32_e32 v159, 4, v152
	v_lshrrev_b32_e32 v160, 3, v158
	v_mul_u32_u24_e32 v160, 3, v160
	v_xor_b32_e32 v160, v159, v160
	v_lshlrev_b32_e32 v160, 4, v160
	v_lshl_add_u32 v160, v158, 6, v160
	v_lshrrev_b32_e32 v161, 1, v153
	v_and_b32_e32 v162, 1, v153
	v_lshl_add_u32 v209, v161, 12, v160
	v_lshl_add_u32 v210, v162, 13, v160
	s_lshl_b32 s12, s11, 12
	s_lshl_b32 s11, s11, 11
	s_add_u32 m0, s11, 0x0
	s_nop 0
	global_load_lds_dwordx4 v203, s[2:3]
	s_add_u32 m0, s11, 0x400
	s_nop 0
	global_load_lds_dwordx4 v204, s[2:3]
	s_add_u32 m0, s12, 0x2000
	s_nop 0
	global_load_lds_dwordx4 v205, s[4:5]
	s_add_u32 m0, s12, 0x2400
	s_nop 0
	global_load_lds_dwordx4 v206, s[4:5]
	s_add_u32 m0, s12, 0x2800
	s_nop 0
	global_load_lds_dwordx4 v207, s[4:5]
	s_add_u32 m0, s12, 0x2c00
	s_nop 0
	global_load_lds_dwordx4 v208, s[4:5]
	s_add_u32 s2, s2, 0x40
	s_addc_u32 s3, s3, 0
	s_add_u32 s4, s4, 0x40
	s_addc_u32 s5, s5, 0
	s_add_u32 m0, s11, 0x6000
	s_nop 0
	global_load_lds_dwordx4 v203, s[2:3]
	s_add_u32 m0, s11, 0x6400
	s_nop 0
	global_load_lds_dwordx4 v204, s[2:3]
	s_add_u32 m0, s12, 0x8000
	s_nop 0
	global_load_lds_dwordx4 v205, s[4:5]
	s_add_u32 m0, s12, 0x8400
	s_nop 0
	global_load_lds_dwordx4 v206, s[4:5]
	s_add_u32 m0, s12, 0x8800
	s_nop 0
	global_load_lds_dwordx4 v207, s[4:5]
	s_add_u32 m0, s12, 0x8c00
	s_nop 0
	global_load_lds_dwordx4 v208, s[4:5]
	s_add_u32 s2, s2, 0x40
	s_addc_u32 s3, s3, 0
	s_add_u32 s4, s4, 0x40
	s_addc_u32 s5, s5, 0
	v_mov_b32_e32 v172, 0
	v_mov_b32_e32 v173, 0
	v_mov_b32_e32 v174, 0
	v_mov_b32_e32 v175, 0
	v_mov_b32_e32 v168, 0
	v_mov_b32_e32 v169, 0
	v_mov_b32_e32 v170, 0
	v_mov_b32_e32 v171, 0
	v_mov_b32_e32 v116, 0
	v_mov_b32_e32 v117, 0
	v_mov_b32_e32 v118, 0
	v_mov_b32_e32 v119, 0
	v_mov_b32_e32 v112, 0
	v_mov_b32_e32 v113, 0
	v_mov_b32_e32 v114, 0
	v_mov_b32_e32 v115, 0
	v_mov_b32_e32 v108, 0
	v_mov_b32_e32 v109, 0
	v_mov_b32_e32 v110, 0
	v_mov_b32_e32 v111, 0
	v_mov_b32_e32 v104, 0
	v_mov_b32_e32 v105, 0
	v_mov_b32_e32 v106, 0
	v_mov_b32_e32 v107, 0
	v_mov_b32_e32 v100, 0
	v_mov_b32_e32 v101, 0
	v_mov_b32_e32 v102, 0
	v_mov_b32_e32 v103, 0
	v_mov_b32_e32 v96, 0
	v_mov_b32_e32 v97, 0
	v_mov_b32_e32 v98, 0
	v_mov_b32_e32 v99, 0
	v_mov_b32_e32 v92, 0
	v_mov_b32_e32 v93, 0
	v_mov_b32_e32 v94, 0
	v_mov_b32_e32 v95, 0
	v_mov_b32_e32 v88, 0
	v_mov_b32_e32 v89, 0
	v_mov_b32_e32 v90, 0
	v_mov_b32_e32 v91, 0
	v_mov_b32_e32 v84, 0
	v_mov_b32_e32 v85, 0
	v_mov_b32_e32 v86, 0
	v_mov_b32_e32 v87, 0
	v_mov_b32_e32 v80, 0
	v_mov_b32_e32 v81, 0
	v_mov_b32_e32 v82, 0
	v_mov_b32_e32 v83, 0
	v_mov_b32_e32 v76, 0
	v_mov_b32_e32 v77, 0
	v_mov_b32_e32 v78, 0
	v_mov_b32_e32 v79, 0
	v_mov_b32_e32 v72, 0
	v_mov_b32_e32 v73, 0
	v_mov_b32_e32 v74, 0
	v_mov_b32_e32 v75, 0
	v_mov_b32_e32 v68, 0
	v_mov_b32_e32 v69, 0
	v_mov_b32_e32 v70, 0
	v_mov_b32_e32 v71, 0
	v_mov_b32_e32 v64, 0
	v_mov_b32_e32 v65, 0
	v_mov_b32_e32 v66, 0
	v_mov_b32_e32 v67, 0
	v_mov_b32_e32 v60, 0
	v_mov_b32_e32 v61, 0
	v_mov_b32_e32 v62, 0
	v_mov_b32_e32 v63, 0
	v_mov_b32_e32 v56, 0
	v_mov_b32_e32 v57, 0
	v_mov_b32_e32 v58, 0
	v_mov_b32_e32 v59, 0
	v_mov_b32_e32 v52, 0
	v_mov_b32_e32 v53, 0
	v_mov_b32_e32 v54, 0
	v_mov_b32_e32 v55, 0
	v_mov_b32_e32 v48, 0
	v_mov_b32_e32 v49, 0
	v_mov_b32_e32 v50, 0
	v_mov_b32_e32 v51, 0
	v_mov_b32_e32 v44, 0
	v_mov_b32_e32 v45, 0
	v_mov_b32_e32 v46, 0
	v_mov_b32_e32 v47, 0
	v_mov_b32_e32 v40, 0
	v_mov_b32_e32 v41, 0
	v_mov_b32_e32 v42, 0
	v_mov_b32_e32 v43, 0
	v_mov_b32_e32 v36, 0
	v_mov_b32_e32 v37, 0
	v_mov_b32_e32 v38, 0
	v_mov_b32_e32 v39, 0
	v_mov_b32_e32 v32, 0
	v_mov_b32_e32 v33, 0
	v_mov_b32_e32 v34, 0
	v_mov_b32_e32 v35, 0
	v_mov_b32_e32 v28, 0
	v_mov_b32_e32 v29, 0
	v_mov_b32_e32 v30, 0
	v_mov_b32_e32 v31, 0
	v_mov_b32_e32 v24, 0
	v_mov_b32_e32 v25, 0
	v_mov_b32_e32 v26, 0
	v_mov_b32_e32 v27, 0
	v_mov_b32_e32 v20, 0
	v_mov_b32_e32 v21, 0
	v_mov_b32_e32 v22, 0
	v_mov_b32_e32 v23, 0
	v_mov_b32_e32 v16, 0
	v_mov_b32_e32 v17, 0
	v_mov_b32_e32 v18, 0
	v_mov_b32_e32 v19, 0
	v_mov_b32_e32 v12, 0
	v_mov_b32_e32 v13, 0
	v_mov_b32_e32 v14, 0
	v_mov_b32_e32 v15, 0
	v_mov_b32_e32 v8, 0
	v_mov_b32_e32 v9, 0
	v_mov_b32_e32 v10, 0
	v_mov_b32_e32 v11, 0
	v_mov_b32_e32 v4, 0
	v_mov_b32_e32 v5, 0
	v_mov_b32_e32 v6, 0
	v_mov_b32_e32 v7, 0
	v_mov_b32_e32 v0, 0
	v_mov_b32_e32 v1, 0
	v_mov_b32_e32 v2, 0
	v_mov_b32_e32 v3, 0
	s_waitcnt vmcnt(6)
	s_barrier
	ds_read_b128 v[120:123], v209 offset:0
	ds_read_b128 v[124:127], v209 offset:1024
	ds_read_b128 v[128:131], v209 offset:2048
	ds_read_b128 v[132:135], v209 offset:3072
	ds_read_b128 v[152:155], v210 offset:8192
	ds_read_b128 v[156:159], v210 offset:9216
	ds_read_b128 v[160:163], v210 offset:10240
	ds_read_b128 v[164:167], v210 offset:11264
	ds_read_b128 v[176:179], v210 offset:12288
	ds_read_b128 v[180:183], v210 offset:13312
	s_add_u32 m0, s11, 0xc000
	s_nop 0
	global_load_lds_dwordx4 v203, s[2:3]
	s_add_u32 m0, s11, 0xc400
	s_nop 0
	global_load_lds_dwordx4 v204, s[2:3]
	s_add_u32 m0, s12, 0xe000
	s_nop 0
	global_load_lds_dwordx4 v205, s[4:5]
	s_add_u32 m0, s12, 0xe400
	s_nop 0
	global_load_lds_dwordx4 v206, s[4:5]
	s_add_u32 m0, s12, 0xe800
	s_nop 0
	global_load_lds_dwordx4 v207, s[4:5]
	s_add_u32 m0, s12, 0xec00
	s_nop 0
	global_load_lds_dwordx4 v208, s[4:5]
	s_add_u32 s2, s2, 0x40
	s_addc_u32 s3, s3, 0
	s_add_u32 s4, s4, 0x40
	s_addc_u32 s5, s5, 0
	ds_read_b128 v[184:187], v210 offset:14336
	ds_read_b128 v[188:191], v210 offset:15360
	s_waitcnt lgkmcnt(7)
	v_mfma_f32_16x16x32_bf16 v[172:175], v[152:155], v[120:123], v[172:175]
	v_mfma_f32_16x16x32_bf16 v[92:95], v[152:155], v[124:127], v[92:95]
	v_mfma_f32_16x16x32_bf16 v[60:63], v[152:155], v[128:131], v[60:63]
	v_mfma_f32_16x16x32_bf16 v[28:31], v[152:155], v[132:135], v[28:31]
	s_waitcnt lgkmcnt(6)
	v_mfma_f32_16x16x32_bf16 v[168:171], v[156:159], v[120:123], v[168:171]
	v_mfma_f32_16x16x32_bf16 v[88:91], v[156:159], v[124:127], v[88:91]
	v_mfma_f32_16x16x32_bf16 v[56:59], v[156:159], v[128:131], v[56:59]
	v_mfma_f32_16x16x32_bf16 v[24:27], v[156:159], v[132:135], v[24:27]
	s_waitcnt lgkmcnt(5)
	v_mfma_f32_16x16x32_bf16 v[116:119], v[160:163], v[120:123], v[116:119]
	v_mfma_f32_16x16x32_bf16 v[84:87], v[160:163], v[124:127], v[84:87]
	v_mfma_f32_16x16x32_bf16 v[52:55], v[160:163], v[128:131], v[52:55]
	v_mfma_f32_16x16x32_bf16 v[20:23], v[160:163], v[132:135], v[20:23]
	s_waitcnt lgkmcnt(4)
	v_mfma_f32_16x16x32_bf16 v[112:115], v[164:167], v[120:123], v[112:115]
	v_mfma_f32_16x16x32_bf16 v[80:83], v[164:167], v[124:127], v[80:83]
	v_mfma_f32_16x16x32_bf16 v[48:51], v[164:167], v[128:131], v[48:51]
	v_mfma_f32_16x16x32_bf16 v[16:19], v[164:167], v[132:135], v[16:19]
	s_waitcnt lgkmcnt(3)
	v_mfma_f32_16x16x32_bf16 v[108:111], v[176:179], v[120:123], v[108:111]
	v_mfma_f32_16x16x32_bf16 v[76:79], v[176:179], v[124:127], v[76:79]
	v_mfma_f32_16x16x32_bf16 v[44:47], v[176:179], v[128:131], v[44:47]
	v_mfma_f32_16x16x32_bf16 v[12:15], v[176:179], v[132:135], v[12:15]
	s_waitcnt lgkmcnt(2)
	v_mfma_f32_16x16x32_bf16 v[104:107], v[180:183], v[120:123], v[104:107]
	v_mfma_f32_16x16x32_bf16 v[72:75], v[180:183], v[124:127], v[72:75]
	v_mfma_f32_16x16x32_bf16 v[40:43], v[180:183], v[128:131], v[40:43]
	v_mfma_f32_16x16x32_bf16 v[8:11], v[180:183], v[132:135], v[8:11]
	s_waitcnt lgkmcnt(0)
	s_mov_b32 s13, 5

	.amdhsa_kernel _Z4mega1P
		.amdhsa_group_segment_fixed_size 73728
		.amdhsa_private_segment_fixed_size 0
		.amdhsa_kernarg_size 640
		.amdhsa_user_sgpr_count 2
		.amdhsa_user_sgpr_dispatch_ptr 0
		.amdhsa_user_sgpr_queue_ptr 0
		.amdhsa_user_sgpr_kernarg_segment_ptr 1
		.amdhsa_user_sgpr_dispatch_id 0
		.amdhsa_user_sgpr_kernarg_preload_length 0
		.amdhsa_user_sgpr_kernarg_preload_offset 0
		.amdhsa_user_sgpr_private_segment_size 0
		.amdhsa_uses_dynamic_stack 0
		.amdhsa_enable_private_segment 0
		.amdhsa_system_sgpr_workgroup_id_x 1
		.amdhsa_system_sgpr_workgroup_id_y 0
		.amdhsa_system_sgpr_workgroup_id_z 0
		.amdhsa_system_sgpr_workgroup_info 0
		.amdhsa_system_vgpr_workitem_id 2
		.amdhsa_next_free_vgpr 256
		.amdhsa_next_free_sgpr 102
		.amdhsa_accum_offset 256
		.amdhsa_reserve_vcc 1
		.amdhsa_float_round_mode_32 0
		.amdhsa_float_round_mode_16_64 0
		.amdhsa_float_denorm_mode_32 3
		.amdhsa_float_denorm_mode_16_64 3
		.amdhsa_dx10_clamp 1
		.amdhsa_ieee_mode 1
		.amdhsa_fp16_overflow 0
		.amdhsa_tg_split 0
		.amdhsa_exception_fp_ieee_invalid_op 0
		.amdhsa_exception_fp_denorm_src 0
		.amdhsa_exception_fp_ieee_div_zero 0
		.amdhsa_exception_fp_ieee_overflow 0
		.amdhsa_exception_fp_ieee_underflow 0
		.amdhsa_exception_fp_ieee_inexact 0
		.amdhsa_exception_int_div_zero 0
	.end_amdhsa_kernel

amdhsa.kernels:
  - .agpr_count:     0
    .args:
      - .offset:         0
        .size:           384
        .value_kind:     by_value
      - .offset:         384
        .size:           4
        .value_kind:     hidden_block_count_x
      - .offset:         388
        .size:           4
        .value_kind:     hidden_block_count_y
      - .offset:         392
        .size:           4
        .value_kind:     hidden_block_count_z
      - .offset:         396
        .size:           2
        .value_kind:     hidden_group_size_x
      - .offset:         398
        .size:           2
        .value_kind:     hidden_group_size_y
      - .offset:         400
        .size:           2
        .value_kind:     hidden_group_size_z
      - .offset:         402
        .size:           2
        .value_kind:     hidden_remainder_x
      - .offset:         404
        .size:           2
        .value_kind:     hidden_remainder_y
      - .offset:         406
        .size:           2
        .value_kind:     hidden_remainder_z
      - .offset:         424
        .size:           8
        .value_kind:     hidden_global_offset_x
      - .offset:         432
        .size:           8
        .value_kind:     hidden_global_offset_y
      - .offset:         440
        .size:           8
        .value_kind:     hidden_global_offset_z
      - .offset:         448
        .size:           2
        .value_kind:     hidden_grid_dims
      - .offset:         472
        .size:           8
        .value_kind:     hidden_multigrid_sync_arg
    .group_segment_fixed_size: 73728
    .kernarg_segment_align: 8
    .kernarg_segment_size: 640
    .language:       OpenCL C
    .language_version:
      - 2
      - 0
    .max_flat_workgroup_size: 256
    .name:           _Z4mega1P
    .private_segment_fixed_size: 0
    .sgpr_count:     108
    .sgpr_spill_count: 273
    .symbol:         _Z4mega1P.kd
    .uniform_work_group_size: 1
    .uses_dynamic_stack: false
    .vgpr_count:     256
    .vgpr_spill_count: 0
    .wavefront_size: 64
